# K-loop LDS-DMA loads use SGPR base + per-unit VGPR offsets (no per-load 64-bit address adds; P1 loop unchanged), combined with czero + p8pk + p1pk
# speedup vs baseline: 1.0036x; 1.0036x over previous
; #define PG8_STAGE(bufoff, gbase, voff) do { _Pragma("unroll") for (int _i = 0; _i < 2; ++_i) \
;         __builtin_amdgcn_global_load_lds((const unsigned*)((const char*)(gbase) + (voff)[_i]), (PG8_LAS unsigned*)(lds + (bufoff) + ldsw + _i * 8192), 16, 0, 0); } while (0)
; #define PG8_LDA(dst, b, h) do { _Pragma("unroll") for (int m = 0; m < 4; ++m) _Pragma("unroll") for (int k = 0; k < 2; ++k) dst[m][k] = *(const PG8_LAS bf16x8*)(lds + PG8_SA(b, h) + aoff + m * 2048 + k * 1024); } while (0)
; #define PG8_LDB(dst, b, h) do { _Pragma("unroll") for (int n = 0; n < 2; ++n) _Pragma("unroll") for (int k = 0; k < 2; ++k) dst[n][k] = *(const PG8_LAS bf16x8*)(lds + PG8_SB(b, h) + boff + n * 2048 + k * 1024); } while (0)
; #define PG8_MMA(ai, bj, At, Bt) do { __builtin_amdgcn_s_setprio(1); _Pragma("unroll") for (int m = 0; m < 4; ++m) _Pragma("unroll") for (int n = 0; n < 2; ++n) _Pragma("unroll") for (int k = 0; k < 2; ++k) \
;         acc[ai][bj][m][n] = __builtin_amdgcn_mfma_f32_16x16x32_bf16(Bt[n][k], At[m][k], acc[ai][bj][m][n], 0, 0, 0); __builtin_amdgcn_s_setprio(0); } while (0)
; #define PG8_WAIT_V(n) asm volatile("s_waitcnt vmcnt(" #n ")" ::: "memory")
; #define PG8_WAIT_L(n) asm volatile("s_waitcnt lgkmcnt(" #n ")" ::: "memory")
; #define PG8_BAR __builtin_amdgcn_s_barrier()
; #define PG8_SCHED __builtin_amdgcn_sched_barrier(0)
; template <class Epi, class Sched, bool ALIGN_EPI = false, bool SP2 = false>
; __device__ __forceinline__ void gemm_phase(PG8_LAS unsigned char* lds, const Gemm g, const Sched& S, const Epi& E) {
;     ...
;             PG8_LDB(B0, 0, 0); PG8_LDB(B1, 0, 1); PG8_SCHED; PG8_LDA(At, 0, 0); PG8_STAGE(PG8_SA(1, 1), a1 + hstep, voffA);
;             PG8_WAIT_V(8); PG8_WAIT_L(0); PG8_BAR; PG8_MMA(0, 0, At, B0); PG8_MMA(0, 1, At, B1); PG8_BAR; PG8_SCHED;
;             PG8_LDA(At, 0, 1); PG8_STAGE(PG8_SB(0, 0), b2, voffB); PG8_STAGE(PG8_SB(0, 1), b2 + hstep, voffB); PG8_STAGE(PG8_SA(0, 0), a2, voffA);
;             PG8_WAIT_V(8); PG8_WAIT_L(0); PG8_BAR; PG8_MMA(1, 0, At, B0); PG8_MMA(1, 1, At, B1); PG8_BAR; PG8_SCHED;
.Lcz_go_460:
	s_add_u32 s0, s62, 0x80
	s_addc_u32 s1, s63, 0
	s_add_u32 s62, s60, 0x100
	s_addc_u32 s63, s61, 0
	s_mov_b32 s60, 0
	v_add_u32_e32 v150, s8, v132
	v_add_u32_e32 v151, s8, v128
	v_add_u32_e32 v198, s8, v134
	v_add_u32_e32 v199, s8, v130
	v_add_u32_e32 v222, 0x80, v132
	v_add_u32_e32 v223, 0x80, v128
	v_add_u32_e32 v224, 0x80, v150
	v_add_u32_e32 v225, 0x80, v151
	v_add_u32_e32 v226, 0x80, v134
	v_add_u32_e32 v227, 0x80, v130
	ds_read_b128 v[146:149], v154
	ds_read_b128 v[158:161], v154 offset:1024
	ds_read_b128 v[162:165], v154 offset:2048
	ds_read_b128 v[166:169], v154 offset:3072
	ds_read_b128 v[170:173], v155
	ds_read_b128 v[174:177], v155 offset:1024
	ds_read_b128 v[178:181], v155 offset:2048
	ds_read_b128 v[182:185], v155 offset:3072
	s_add_i32 s97, s60, 2
	s_add_u32 s16, s0, 0x80
	s_addc_u32 s17, s1, 0
	s_cmp_eq_u32 s80, s60
	s_cselect_b32 s60, s56, s16
	s_cselect_b32 s61, s57, s17
	s_cselect_b32 vcc_hi, s59, s63
	s_cselect_b32 vcc_lo, s58, s62
	s_add_i32 m0, s72, 0xc000
	ds_read_b128 v[186:189], v156
	ds_read_b128 v[190:193], v156 offset:1024
	ds_read_b128 v[194:197], v156 offset:2048
	ds_read_b128 v[202:205], v156 offset:3072
	ds_read_b128 v[206:209], v156 offset:4096
	ds_read_b128 v[210:213], v156 offset:5120
	ds_read_b128 v[214:217], v156 offset:6144
	ds_read_b128 v[218:221], v156 offset:7168
	global_load_lds_dwordx4 v138, s[0:1]
	s_add_i32 m0, s72, 0xe000
	s_nop 0
	global_load_lds_dwordx4 v140, s[0:1]
	s_waitcnt vmcnt(8)
	s_waitcnt lgkmcnt(0)
	s_barrier
	s_setprio 1
	s_waitcnt lgkmcnt(0)
	v_mfma_f32_16x16x32_bf16 v[120:123], v[146:149], v[186:189], 0
	v_mfma_f32_16x16x32_bf16 v[124:127], v[162:165], v[186:189], 0
	v_mfma_f32_16x16x32_bf16 v[108:111], v[146:149], v[194:197], 0
	v_mfma_f32_16x16x32_bf16 v[104:107], v[162:165], v[194:197], 0
	v_mfma_f32_16x16x32_bf16 v[92:95], v[146:149], v[206:209], 0
	v_mfma_f32_16x16x32_bf16 v[88:91], v[162:165], v[206:209], 0
	v_mfma_f32_16x16x32_bf16 v[76:79], v[146:149], v[214:217], 0
	v_mfma_f32_16x16x32_bf16 v[72:75], v[162:165], v[214:217], 0
	v_mfma_f32_16x16x32_bf16 v[120:123], v[158:161], v[190:193], v[120:123]
	v_mfma_f32_16x16x32_bf16 v[124:127], v[166:169], v[190:193], v[124:127]
	v_mfma_f32_16x16x32_bf16 v[108:111], v[158:161], v[202:205], v[108:111]
	v_mfma_f32_16x16x32_bf16 v[104:107], v[166:169], v[202:205], v[104:107]
	v_mfma_f32_16x16x32_bf16 v[92:95], v[158:161], v[210:213], v[92:95]
	v_mfma_f32_16x16x32_bf16 v[88:91], v[166:169], v[210:213], v[88:91]
	v_mfma_f32_16x16x32_bf16 v[76:79], v[158:161], v[218:221], v[76:79]
	v_mfma_f32_16x16x32_bf16 v[72:75], v[166:169], v[218:221], v[72:75]
	s_setprio 0
	s_setprio 1
	v_mfma_f32_16x16x32_bf16 v[116:119], v[170:173], v[186:189], 0
	v_mfma_f32_16x16x32_bf16 v[112:115], v[178:181], v[186:189], 0
	v_mfma_f32_16x16x32_bf16 v[100:103], v[170:173], v[194:197], 0
	v_mfma_f32_16x16x32_bf16 v[96:99], v[178:181], v[194:197], 0
	v_mfma_f32_16x16x32_bf16 v[84:87], v[170:173], v[206:209], 0
	v_mfma_f32_16x16x32_bf16 v[80:83], v[178:181], v[206:209], 0
	v_mfma_f32_16x16x32_bf16 v[68:71], v[170:173], v[214:217], 0
	v_mfma_f32_16x16x32_bf16 v[64:67], v[178:181], v[214:217], 0
	v_mfma_f32_16x16x32_bf16 v[116:119], v[174:177], v[190:193], v[116:119]
	v_mfma_f32_16x16x32_bf16 v[112:115], v[182:185], v[190:193], v[112:115]
	v_mfma_f32_16x16x32_bf16 v[100:103], v[174:177], v[202:205], v[100:103]
	v_mfma_f32_16x16x32_bf16 v[96:99], v[182:185], v[202:205], v[96:99]
	v_mfma_f32_16x16x32_bf16 v[84:87], v[174:177], v[210:213], v[84:87]
	v_mfma_f32_16x16x32_bf16 v[80:83], v[182:185], v[210:213], v[80:83]
	v_mfma_f32_16x16x32_bf16 v[68:71], v[174:177], v[218:221], v[68:71]
	v_mfma_f32_16x16x32_bf16 v[64:67], v[182:185], v[218:221], v[64:67]
	s_setprio 0
	s_barrier
	s_add_i32 s16, s83, s49
	s_mov_b32 m0, s16
	ds_read_b128 v[186:189], v156 offset:16384
	ds_read_b128 v[190:193], v156 offset:17408
	ds_read_b128 v[194:197], v156 offset:18432
	ds_read_b128 v[202:205], v156 offset:19456
	ds_read_b128 v[206:209], v156 offset:20480
	ds_read_b128 v[210:213], v156 offset:21504
	ds_read_b128 v[214:217], v156 offset:22528
	ds_read_b128 v[218:221], v156 offset:23552
	global_load_lds_dwordx4 v132, vcc
	s_add_i32 m0, s16, 0x2000
	s_add_i32 s16, s84, s49
	global_load_lds_dwordx4 v128, vcc
	s_mov_b32 m0, s16
	s_nop 0
	global_load_lds_dwordx4 v150, vcc
	s_add_i32 m0, s16, 0x2000
	s_nop 0
	global_load_lds_dwordx4 v151, vcc
	s_mov_b32 m0, s72
	s_nop 0
	global_load_lds_dwordx4 v134, s[60:61]
	s_mov_b32 m0, s73
	s_nop 0
	global_load_lds_dwordx4 v130, s[60:61]
	s_waitcnt vmcnt(8)
	s_waitcnt lgkmcnt(0)
	s_barrier
; #define PG8_STAGE(bufoff, gbase, voff) do { _Pragma("unroll") for (int _i = 0; _i < 2; ++_i) \
;         __builtin_amdgcn_global_load_lds((const unsigned*)((const char*)(gbase) + (voff)[_i]), (PG8_LAS unsigned*)(lds + (bufoff) + ldsw + _i * 8192), 16, 0, 0); } while (0)
; #define PG8_LDA(dst, b, h) do { _Pragma("unroll") for (int m = 0; m < 4; ++m) _Pragma("unroll") for (int k = 0; k < 2; ++k) dst[m][k] = *(const PG8_LAS bf16x8*)(lds + PG8_SA(b, h) + aoff + m * 2048 + k * 1024); } while (0)
; #define PG8_LDB(dst, b, h) do { _Pragma("unroll") for (int n = 0; n < 2; ++n) _Pragma("unroll") for (int k = 0; k < 2; ++k) dst[n][k] = *(const PG8_LAS bf16x8*)(lds + PG8_SB(b, h) + boff + n * 2048 + k * 1024); } while (0)
; #define PG8_MMA(ai, bj, At, Bt) do { __builtin_amdgcn_s_setprio(1); _Pragma("unroll") for (int m = 0; m < 4; ++m) _Pragma("unroll") for (int n = 0; n < 2; ++n) _Pragma("unroll") for (int k = 0; k < 2; ++k) \
;         acc[ai][bj][m][n] = __builtin_amdgcn_mfma_f32_16x16x32_bf16(Bt[n][k], At[m][k], acc[ai][bj][m][n], 0, 0, 0); __builtin_amdgcn_s_setprio(0); } while (0)
; #define PG8_WAIT_V(n) asm volatile("s_waitcnt vmcnt(" #n ")" ::: "memory")
; #define PG8_WAIT_L(n) asm volatile("s_waitcnt lgkmcnt(" #n ")" ::: "memory")
; #define PG8_BAR __builtin_amdgcn_s_barrier()
; #define PG8_SCHED __builtin_amdgcn_sched_barrier(0)
; template <class Epi, class Sched, bool ALIGN_EPI = false, bool SP2 = false>
; __device__ __forceinline__ void gemm_phase(PG8_LAS unsigned char* lds, const Gemm g, const Sched& S, const Epi& E) {
;     ...
;             PG8_WAIT_V(8); PG8_WAIT_L(0); PG8_BAR; PG8_MMA(1, 0, At, B0); PG8_MMA(1, 1, At, B1); PG8_BAR; PG8_SCHED;
;             PG8_LDB(B0, 1, 0); PG8_LDB(B1, 1, 1); PG8_SCHED; PG8_LDA(At, 1, 0); PG8_STAGE(PG8_SA(0, 1), a2 + hstep, voffA);
;             PG8_WAIT_V(8); PG8_WAIT_L(0); PG8_BAR; PG8_MMA(0, 0, At, B0); PG8_MMA(0, 1, At, B1); PG8_BAR; PG8_SCHED;
	s_setprio 1
	s_waitcnt lgkmcnt(0)
	v_mfma_f32_16x16x32_bf16 v[60:63], v[146:149], v[186:189], 0
	v_mfma_f32_16x16x32_bf16 v[56:59], v[162:165], v[186:189], 0
	v_mfma_f32_16x16x32_bf16 v[44:47], v[146:149], v[194:197], 0
	v_mfma_f32_16x16x32_bf16 v[40:43], v[162:165], v[194:197], 0
	v_mfma_f32_16x16x32_bf16 v[28:31], v[146:149], v[206:209], 0
	v_mfma_f32_16x16x32_bf16 v[24:27], v[162:165], v[206:209], 0
	v_mfma_f32_16x16x32_bf16 v[12:15], v[146:149], v[214:217], 0
	v_mfma_f32_16x16x32_bf16 v[8:11], v[162:165], v[214:217], 0
	v_mfma_f32_16x16x32_bf16 v[60:63], v[158:161], v[190:193], v[60:63]
	v_mfma_f32_16x16x32_bf16 v[56:59], v[166:169], v[190:193], v[56:59]
	v_mfma_f32_16x16x32_bf16 v[44:47], v[158:161], v[202:205], v[44:47]
	v_mfma_f32_16x16x32_bf16 v[40:43], v[166:169], v[202:205], v[40:43]
	v_mfma_f32_16x16x32_bf16 v[28:31], v[158:161], v[210:213], v[28:31]
	v_mfma_f32_16x16x32_bf16 v[24:27], v[166:169], v[210:213], v[24:27]
	v_mfma_f32_16x16x32_bf16 v[12:15], v[158:161], v[218:221], v[12:15]
	v_mfma_f32_16x16x32_bf16 v[8:11], v[166:169], v[218:221], v[8:11]
	s_setprio 0
	s_setprio 1
	v_mfma_f32_16x16x32_bf16 v[52:55], v[170:173], v[186:189], 0
	v_mfma_f32_16x16x32_bf16 v[48:51], v[178:181], v[186:189], 0
	v_mfma_f32_16x16x32_bf16 v[36:39], v[170:173], v[194:197], 0
	v_mfma_f32_16x16x32_bf16 v[32:35], v[178:181], v[194:197], 0
	v_mfma_f32_16x16x32_bf16 v[20:23], v[170:173], v[206:209], 0
	v_mfma_f32_16x16x32_bf16 v[16:19], v[178:181], v[206:209], 0
	v_mfma_f32_16x16x32_bf16 v[4:7], v[170:173], v[214:217], 0
	v_mfma_f32_16x16x32_bf16 v[0:3], v[178:181], v[214:217], 0
	v_mfma_f32_16x16x32_bf16 v[52:55], v[174:177], v[190:193], v[52:55]
	v_mfma_f32_16x16x32_bf16 v[48:51], v[182:185], v[190:193], v[48:51]
	v_mfma_f32_16x16x32_bf16 v[36:39], v[174:177], v[202:205], v[36:39]
	v_mfma_f32_16x16x32_bf16 v[32:35], v[182:185], v[202:205], v[32:35]
	v_mfma_f32_16x16x32_bf16 v[20:23], v[174:177], v[210:213], v[20:23]
	v_mfma_f32_16x16x32_bf16 v[16:19], v[182:185], v[210:213], v[16:19]
	v_mfma_f32_16x16x32_bf16 v[4:7], v[174:177], v[218:221], v[4:7]
	v_mfma_f32_16x16x32_bf16 v[0:3], v[182:185], v[218:221], v[0:3]
	s_setprio 0
	s_barrier
	s_add_i32 s16, 0, 0x18000
	s_add_i32 s17, 0, 0x1c000
	v_add_u32_e32 v166, s16, v153
	v_add_u32_e32 v182, s17, v153
	ds_read_b128 v[146:149], v166
	ds_read_b128 v[158:161], v166 offset:1024
	ds_read_b128 v[162:165], v166 offset:2048
	ds_read_b128 v[166:169], v166 offset:3072
	ds_read_b128 v[170:173], v182
	ds_read_b128 v[174:177], v182 offset:1024
	ds_read_b128 v[178:181], v182 offset:2048
	ds_read_b128 v[182:185], v182 offset:3072
	s_mov_b32 m0, s74
	ds_read_b128 v[186:189], v156 offset:32768
	ds_read_b128 v[190:193], v156 offset:33792
	ds_read_b128 v[194:197], v156 offset:34816
	ds_read_b128 v[202:205], v156 offset:35840
	ds_read_b128 v[206:209], v156 offset:36864
	ds_read_b128 v[210:213], v156 offset:37888
	ds_read_b128 v[214:217], v156 offset:38912
	ds_read_b128 v[218:221], v156 offset:39936
	global_load_lds_dwordx4 v198, s[60:61]
	s_mov_b32 m0, s75
	s_nop 0
	global_load_lds_dwordx4 v199, s[60:61]
	s_waitcnt vmcnt(8)
	s_waitcnt lgkmcnt(0)
	s_barrier
	s_setprio 1
	s_waitcnt lgkmcnt(0)
	v_mfma_f32_16x16x32_bf16 v[120:123], v[146:149], v[186:189], v[120:123]
	v_mfma_f32_16x16x32_bf16 v[124:127], v[162:165], v[186:189], v[124:127]
	v_mfma_f32_16x16x32_bf16 v[108:111], v[146:149], v[194:197], v[108:111]
	v_mfma_f32_16x16x32_bf16 v[104:107], v[162:165], v[194:197], v[104:107]
	v_mfma_f32_16x16x32_bf16 v[92:95], v[146:149], v[206:209], v[92:95]
	v_mfma_f32_16x16x32_bf16 v[88:91], v[162:165], v[206:209], v[88:91]
	v_mfma_f32_16x16x32_bf16 v[76:79], v[146:149], v[214:217], v[76:79]
	v_mfma_f32_16x16x32_bf16 v[72:75], v[162:165], v[214:217], v[72:75]
	v_mfma_f32_16x16x32_bf16 v[120:123], v[158:161], v[190:193], v[120:123]
	v_mfma_f32_16x16x32_bf16 v[124:127], v[166:169], v[190:193], v[124:127]
	v_mfma_f32_16x16x32_bf16 v[108:111], v[158:161], v[202:205], v[108:111]
	v_mfma_f32_16x16x32_bf16 v[104:107], v[166:169], v[202:205], v[104:107]
	v_mfma_f32_16x16x32_bf16 v[92:95], v[158:161], v[210:213], v[92:95]
	v_mfma_f32_16x16x32_bf16 v[88:91], v[166:169], v[210:213], v[88:91]
	v_mfma_f32_16x16x32_bf16 v[76:79], v[158:161], v[218:221], v[76:79]
	v_mfma_f32_16x16x32_bf16 v[72:75], v[166:169], v[218:221], v[72:75]
	s_setprio 0
	s_setprio 1
	v_mfma_f32_16x16x32_bf16 v[116:119], v[170:173], v[186:189], v[116:119]
	v_mfma_f32_16x16x32_bf16 v[112:115], v[178:181], v[186:189], v[112:115]
	v_mfma_f32_16x16x32_bf16 v[100:103], v[170:173], v[194:197], v[100:103]
	v_mfma_f32_16x16x32_bf16 v[96:99], v[178:181], v[194:197], v[96:99]
	v_mfma_f32_16x16x32_bf16 v[84:87], v[170:173], v[206:209], v[84:87]
	v_mfma_f32_16x16x32_bf16 v[80:83], v[178:181], v[206:209], v[80:83]
	v_mfma_f32_16x16x32_bf16 v[68:71], v[170:173], v[214:217], v[68:71]
	v_mfma_f32_16x16x32_bf16 v[64:67], v[178:181], v[214:217], v[64:67]
	v_mfma_f32_16x16x32_bf16 v[116:119], v[174:177], v[190:193], v[116:119]
	v_mfma_f32_16x16x32_bf16 v[112:115], v[182:185], v[190:193], v[112:115]
	v_mfma_f32_16x16x32_bf16 v[100:103], v[174:177], v[202:205], v[100:103]
	v_mfma_f32_16x16x32_bf16 v[96:99], v[182:185], v[202:205], v[96:99]
	v_mfma_f32_16x16x32_bf16 v[84:87], v[174:177], v[210:213], v[84:87]
	v_mfma_f32_16x16x32_bf16 v[80:83], v[182:185], v[210:213], v[80:83]
	v_mfma_f32_16x16x32_bf16 v[68:71], v[174:177], v[218:221], v[68:71]
	v_mfma_f32_16x16x32_bf16 v[64:67], v[182:185], v[218:221], v[64:67]
	s_setprio 0
	s_barrier
; #define PG8_STAGE(bufoff, gbase, voff) do { _Pragma("unroll") for (int _i = 0; _i < 2; ++_i) \
;         __builtin_amdgcn_global_load_lds((const unsigned*)((const char*)(gbase) + (voff)[_i]), (PG8_LAS unsigned*)(lds + (bufoff) + ldsw + _i * 8192), 16, 0, 0); } while (0)
; #define PG8_LDA(dst, b, h) do { _Pragma("unroll") for (int m = 0; m < 4; ++m) _Pragma("unroll") for (int k = 0; k < 2; ++k) dst[m][k] = *(const PG8_LAS bf16x8*)(lds + PG8_SA(b, h) + aoff + m * 2048 + k * 1024); } while (0)
; #define PG8_MMA(ai, bj, At, Bt) do { __builtin_amdgcn_s_setprio(1); _Pragma("unroll") for (int m = 0; m < 4; ++m) _Pragma("unroll") for (int n = 0; n < 2; ++n) _Pragma("unroll") for (int k = 0; k < 2; ++k) \
;         acc[ai][bj][m][n] = __builtin_amdgcn_mfma_f32_16x16x32_bf16(Bt[n][k], At[m][k], acc[ai][bj][m][n], 0, 0, 0); __builtin_amdgcn_s_setprio(0); } while (0)
; #define PG8_WAIT_V(n) asm volatile("s_waitcnt vmcnt(" #n ")" ::: "memory")
; #define PG8_WAIT_L(n) asm volatile("s_waitcnt lgkmcnt(" #n ")" ::: "memory")
; #define PG8_BAR __builtin_amdgcn_s_barrier()
; #define PG8_SCHED __builtin_amdgcn_sched_barrier(0)
; template <class Epi, class Sched, bool ALIGN_EPI = false, bool SP2 = false>
; __device__ __forceinline__ void gemm_phase(PG8_LAS unsigned char* lds, const Gemm g, const Sched& S, const Epi& E) {
;     ...
;         for (int t = 0; t < nt; t += 2) {
;             const bool last = (t == nt - 2);
;             const char* a1 = cA + (size_t)(t + 1) * kstep;
;             const char* a2 = last ? nA : cA + (size_t)(t + 2) * kstep; const char* b2 = last ? nB : cB + (size_t)(t + 2) * kstep;
;             const char* a3 = a2 + kstep; const char* b3 = b2 + kstep;
;     ...
;             PG8_LDA(At, 1, 1); PG8_STAGE(PG8_SB(1, 0), b3, voffB); PG8_STAGE(PG8_SB(1, 1), b3 + hstep, voffB); PG8_STAGE(PG8_SA(1, 0), a3, voffA);
;             PG8_WAIT_V(8); PG8_WAIT_L(0); PG8_BAR; PG8_MMA(1, 0, At, B0); PG8_MMA(1, 1, At, B1); PG8_BAR; PG8_SCHED;
	s_add_i32 s16, s16, s49
	s_mov_b32 m0, s16
	ds_read_b128 v[186:189], v156 offset:49152
	ds_read_b128 v[190:193], v156 offset:50176
	ds_read_b128 v[194:197], v156 offset:51200
	ds_read_b128 v[202:205], v156 offset:52224
	ds_read_b128 v[206:209], v156 offset:53248
	ds_read_b128 v[210:213], v156 offset:54272
	ds_read_b128 v[214:217], v156 offset:55296
	ds_read_b128 v[218:221], v156 offset:56320
	global_load_lds_dwordx4 v222, vcc
	s_add_i32 m0, s16, 0x2000
	s_add_i32 s16, s17, s49
	global_load_lds_dwordx4 v223, vcc
	s_mov_b32 m0, s16
	s_nop 0
	global_load_lds_dwordx4 v224, vcc
	s_add_i32 m0, s16, 0x2000
	s_nop 0
	global_load_lds_dwordx4 v225, vcc
	s_mov_b32 m0, s77
	s_nop 0
	global_load_lds_dwordx4 v226, s[60:61]
	s_mov_b32 m0, s78
	s_nop 0
	global_load_lds_dwordx4 v227, s[60:61]
	s_waitcnt vmcnt(8)
	s_waitcnt lgkmcnt(0)
	s_barrier
	s_setprio 1
	s_waitcnt lgkmcnt(0)
	v_mfma_f32_16x16x32_bf16 v[60:63], v[146:149], v[186:189], v[60:63]
	v_mfma_f32_16x16x32_bf16 v[56:59], v[162:165], v[186:189], v[56:59]
	v_mfma_f32_16x16x32_bf16 v[44:47], v[146:149], v[194:197], v[44:47]
	v_mfma_f32_16x16x32_bf16 v[40:43], v[162:165], v[194:197], v[40:43]
	v_mfma_f32_16x16x32_bf16 v[28:31], v[146:149], v[206:209], v[28:31]
	v_mfma_f32_16x16x32_bf16 v[24:27], v[162:165], v[206:209], v[24:27]
	v_mfma_f32_16x16x32_bf16 v[12:15], v[146:149], v[214:217], v[12:15]
	v_mfma_f32_16x16x32_bf16 v[8:11], v[162:165], v[214:217], v[8:11]
	v_mfma_f32_16x16x32_bf16 v[60:63], v[158:161], v[190:193], v[60:63]
	v_mfma_f32_16x16x32_bf16 v[56:59], v[166:169], v[190:193], v[56:59]
	v_mfma_f32_16x16x32_bf16 v[44:47], v[158:161], v[202:205], v[44:47]
	v_mfma_f32_16x16x32_bf16 v[40:43], v[166:169], v[202:205], v[40:43]
	v_mfma_f32_16x16x32_bf16 v[28:31], v[158:161], v[210:213], v[28:31]
	v_mfma_f32_16x16x32_bf16 v[24:27], v[166:169], v[210:213], v[24:27]
	v_mfma_f32_16x16x32_bf16 v[12:15], v[158:161], v[218:221], v[12:15]
	v_mfma_f32_16x16x32_bf16 v[8:11], v[166:169], v[218:221], v[8:11]
	s_setprio 0
	s_setprio 1
	v_mfma_f32_16x16x32_bf16 v[52:55], v[170:173], v[186:189], v[52:55]
	v_mfma_f32_16x16x32_bf16 v[48:51], v[178:181], v[186:189], v[48:51]
	v_mfma_f32_16x16x32_bf16 v[36:39], v[170:173], v[194:197], v[36:39]
	v_mfma_f32_16x16x32_bf16 v[32:35], v[178:181], v[194:197], v[32:35]
	v_mfma_f32_16x16x32_bf16 v[20:23], v[170:173], v[206:209], v[20:23]
	v_mfma_f32_16x16x32_bf16 v[16:19], v[178:181], v[206:209], v[16:19]
	v_mfma_f32_16x16x32_bf16 v[4:7], v[170:173], v[214:217], v[4:7]
	v_mfma_f32_16x16x32_bf16 v[0:3], v[178:181], v[214:217], v[0:3]
	v_mfma_f32_16x16x32_bf16 v[52:55], v[174:177], v[190:193], v[52:55]
	v_mfma_f32_16x16x32_bf16 v[48:51], v[182:185], v[190:193], v[48:51]
	v_mfma_f32_16x16x32_bf16 v[36:39], v[174:177], v[202:205], v[36:39]
	v_mfma_f32_16x16x32_bf16 v[32:35], v[182:185], v[202:205], v[32:35]
	v_mfma_f32_16x16x32_bf16 v[20:23], v[174:177], v[210:213], v[20:23]
	v_mfma_f32_16x16x32_bf16 v[16:19], v[182:185], v[210:213], v[16:19]
	v_mfma_f32_16x16x32_bf16 v[4:7], v[174:177], v[218:221], v[4:7]
	v_mfma_f32_16x16x32_bf16 v[0:3], v[182:185], v[218:221], v[0:3]
	s_setprio 0
	s_barrier
	s_add_u32 s0, s0, 0x100
	s_addc_u32 s1, s1, 0
	s_add_u32 s62, s62, 0x100
	s_addc_u32 s63, s63, 0
	s_cmp_ge_i32 s97, s79
	s_mov_b32 s60, s97
	s_cbranch_scc1 .LBB0_461

; #define PG8_STAGE(bufoff, gbase, voff) do { _Pragma("unroll") for (int _i = 0; _i < 2; ++_i) \
;         __builtin_amdgcn_global_load_lds((const unsigned*)((const char*)(gbase) + (voff)[_i]), (PG8_LAS unsigned*)(lds + (bufoff) + ldsw + _i * 8192), 16, 0, 0); } while (0)
; #define PG8_LDA(dst, b, h) do { _Pragma("unroll") for (int m = 0; m < 4; ++m) _Pragma("unroll") for (int k = 0; k < 2; ++k) dst[m][k] = *(const PG8_LAS bf16x8*)(lds + PG8_SA(b, h) + aoff + m * 2048 + k * 1024); } while (0)
; #define PG8_LDB(dst, b, h) do { _Pragma("unroll") for (int n = 0; n < 2; ++n) _Pragma("unroll") for (int k = 0; k < 2; ++k) dst[n][k] = *(const PG8_LAS bf16x8*)(lds + PG8_SB(b, h) + boff + n * 2048 + k * 1024); } while (0)
; #define PG8_MMA(ai, bj, At, Bt) do { __builtin_amdgcn_s_setprio(1); _Pragma("unroll") for (int m = 0; m < 4; ++m) _Pragma("unroll") for (int n = 0; n < 2; ++n) _Pragma("unroll") for (int k = 0; k < 2; ++k) \
;         acc[ai][bj][m][n] = __builtin_amdgcn_mfma_f32_16x16x32_bf16(Bt[n][k], At[m][k], acc[ai][bj][m][n], 0, 0, 0); __builtin_amdgcn_s_setprio(0); } while (0)
; #define PG8_WAIT_V(n) asm volatile("s_waitcnt vmcnt(" #n ")" ::: "memory")
; #define PG8_WAIT_L(n) asm volatile("s_waitcnt lgkmcnt(" #n ")" ::: "memory")
; #define PG8_BAR __builtin_amdgcn_s_barrier()
; #define PG8_SCHED __builtin_amdgcn_sched_barrier(0)
; template <class Epi, class Sched, bool ALIGN_EPI = false, bool SP2 = false>
; __device__ __forceinline__ void gemm_phase(PG8_LAS unsigned char* lds, const Gemm g, const Sched& S, const Epi& E) {
;     ...
;             PG8_LDB(B0, 0, 0); PG8_LDB(B1, 0, 1); PG8_SCHED; PG8_LDA(At, 0, 0); PG8_STAGE(PG8_SA(1, 1), a1 + hstep, voffA);
;             PG8_WAIT_V(8); PG8_WAIT_L(0); PG8_BAR; PG8_MMA(0, 0, At, B0); PG8_MMA(0, 1, At, B1); PG8_BAR; PG8_SCHED;
;             PG8_LDA(At, 0, 1); PG8_STAGE(PG8_SB(0, 0), b2, voffB); PG8_STAGE(PG8_SB(0, 1), b2 + hstep, voffB); PG8_STAGE(PG8_SA(0, 0), a2, voffA);
;             PG8_WAIT_V(8); PG8_WAIT_L(0); PG8_BAR; PG8_MMA(1, 0, At, B0); PG8_MMA(1, 1, At, B1); PG8_BAR; PG8_SCHED;
.Lcz_go_535:
	s_add_u32 s58, s58, 0x80
	s_addc_u32 s59, s59, 0
	s_add_u32 s95, s60, 0x100
	s_addc_u32 s96, s61, 0
	s_mov_b32 s60, 0
	v_add_u32_e32 v198, s8, v134
	v_add_u32_e32 v199, s8, v138
	v_add_u32_e32 v226, s8, v132
	v_add_u32_e32 v227, s8, v136
	v_add_u32_e32 v228, 0x80, v134
	v_add_u32_e32 v229, 0x80, v138
	v_add_u32_e32 v230, 0x80, v198
	v_add_u32_e32 v231, 0x80, v199
	v_add_u32_e32 v232, 0x80, v132
	v_add_u32_e32 v233, 0x80, v136
	ds_read_b128 v[128:131], v166
	ds_read_b128 v[156:159], v166 offset:1024
	ds_read_b128 v[160:163], v166 offset:2048
	ds_read_b128 v[170:173], v166 offset:3072
	ds_read_b128 v[174:177], v167
	ds_read_b128 v[178:181], v167 offset:1024
	ds_read_b128 v[182:185], v167 offset:2048
	ds_read_b128 v[186:189], v167 offset:3072
	s_add_i32 s97, s60, 2
	s_add_u32 s16, s58, 0x80
	s_addc_u32 s17, s59, 0
	s_cmp_eq_u32 s76, s60
	s_cselect_b32 s60, s0, s16
	s_cselect_b32 s61, s1, s17
	s_cselect_b32 vcc_hi, s57, s96
	s_cselect_b32 vcc_lo, s56, s95
	s_add_i32 m0, s62, 0xc000
	ds_read_b128 v[190:193], v168
	ds_read_b128 v[194:197], v168 offset:1024
	ds_read_b128 v[202:205], v168 offset:2048
	ds_read_b128 v[206:209], v168 offset:3072
	ds_read_b128 v[210:213], v168 offset:4096
	ds_read_b128 v[214:217], v168 offset:5120
	ds_read_b128 v[218:221], v168 offset:6144
	ds_read_b128 v[222:225], v168 offset:7168
	global_load_lds_dwordx4 v148, s[58:59]
	s_add_i32 m0, s62, 0xe000
	s_nop 0
	global_load_lds_dwordx4 v150, s[58:59]
	s_waitcnt vmcnt(8)
	s_waitcnt lgkmcnt(0)
	s_barrier
	s_setprio 1
	s_waitcnt lgkmcnt(0)
	v_mfma_f32_16x16x32_bf16 v[120:123], v[128:131], v[190:193], 0
	v_mfma_f32_16x16x32_bf16 v[124:127], v[160:163], v[190:193], 0
	v_mfma_f32_16x16x32_bf16 v[108:111], v[128:131], v[202:205], 0
	v_mfma_f32_16x16x32_bf16 v[104:107], v[160:163], v[202:205], 0
	v_mfma_f32_16x16x32_bf16 v[92:95], v[128:131], v[210:213], 0
	v_mfma_f32_16x16x32_bf16 v[88:91], v[160:163], v[210:213], 0
	v_mfma_f32_16x16x32_bf16 v[76:79], v[128:131], v[218:221], 0
	v_mfma_f32_16x16x32_bf16 v[72:75], v[160:163], v[218:221], 0
	v_mfma_f32_16x16x32_bf16 v[120:123], v[156:159], v[194:197], v[120:123]
	v_mfma_f32_16x16x32_bf16 v[124:127], v[170:173], v[194:197], v[124:127]
	v_mfma_f32_16x16x32_bf16 v[108:111], v[156:159], v[206:209], v[108:111]
	v_mfma_f32_16x16x32_bf16 v[104:107], v[170:173], v[206:209], v[104:107]
	v_mfma_f32_16x16x32_bf16 v[92:95], v[156:159], v[214:217], v[92:95]
	v_mfma_f32_16x16x32_bf16 v[88:91], v[170:173], v[214:217], v[88:91]
	v_mfma_f32_16x16x32_bf16 v[76:79], v[156:159], v[222:225], v[76:79]
	v_mfma_f32_16x16x32_bf16 v[72:75], v[170:173], v[222:225], v[72:75]
	s_setprio 0
	s_setprio 1
	v_mfma_f32_16x16x32_bf16 v[116:119], v[174:177], v[190:193], 0
	v_mfma_f32_16x16x32_bf16 v[112:115], v[182:185], v[190:193], 0
	v_mfma_f32_16x16x32_bf16 v[100:103], v[174:177], v[202:205], 0
	v_mfma_f32_16x16x32_bf16 v[96:99], v[182:185], v[202:205], 0
	v_mfma_f32_16x16x32_bf16 v[84:87], v[174:177], v[210:213], 0
	v_mfma_f32_16x16x32_bf16 v[80:83], v[182:185], v[210:213], 0
	v_mfma_f32_16x16x32_bf16 v[68:71], v[174:177], v[218:221], 0
	v_mfma_f32_16x16x32_bf16 v[64:67], v[182:185], v[218:221], 0
	v_mfma_f32_16x16x32_bf16 v[116:119], v[178:181], v[194:197], v[116:119]
	v_mfma_f32_16x16x32_bf16 v[112:115], v[186:189], v[194:197], v[112:115]
	v_mfma_f32_16x16x32_bf16 v[100:103], v[178:181], v[206:209], v[100:103]
	v_mfma_f32_16x16x32_bf16 v[96:99], v[186:189], v[206:209], v[96:99]
	v_mfma_f32_16x16x32_bf16 v[84:87], v[178:181], v[214:217], v[84:87]
	v_mfma_f32_16x16x32_bf16 v[80:83], v[186:189], v[214:217], v[80:83]
	v_mfma_f32_16x16x32_bf16 v[68:71], v[178:181], v[222:225], v[68:71]
	v_mfma_f32_16x16x32_bf16 v[64:67], v[186:189], v[222:225], v[64:67]
	s_setprio 0
	s_barrier
	s_add_i32 s16, s79, s49
	s_mov_b32 m0, s16
	ds_read_b128 v[190:193], v168 offset:16384
	ds_read_b128 v[194:197], v168 offset:17408
	ds_read_b128 v[202:205], v168 offset:18432
	ds_read_b128 v[206:209], v168 offset:19456
	ds_read_b128 v[210:213], v168 offset:20480
	ds_read_b128 v[214:217], v168 offset:21504
	ds_read_b128 v[218:221], v168 offset:22528
	ds_read_b128 v[222:225], v168 offset:23552
	global_load_lds_dwordx4 v134, vcc
	s_add_i32 m0, s16, 0x2000
	s_add_i32 s16, s80, s49
	global_load_lds_dwordx4 v138, vcc
	s_mov_b32 m0, s16
	s_nop 0
	global_load_lds_dwordx4 v198, vcc
	s_add_i32 m0, s16, 0x2000
	s_nop 0
	global_load_lds_dwordx4 v199, vcc
	s_mov_b32 m0, s62
	s_nop 0
	global_load_lds_dwordx4 v132, s[60:61]
	s_mov_b32 m0, s63
	s_nop 0
	global_load_lds_dwordx4 v136, s[60:61]
	s_waitcnt vmcnt(8)
	s_waitcnt lgkmcnt(0)
	s_barrier
; #define PG8_STAGE(bufoff, gbase, voff) do { _Pragma("unroll") for (int _i = 0; _i < 2; ++_i) \
;         __builtin_amdgcn_global_load_lds((const unsigned*)((const char*)(gbase) + (voff)[_i]), (PG8_LAS unsigned*)(lds + (bufoff) + ldsw + _i * 8192), 16, 0, 0); } while (0)
; #define PG8_LDA(dst, b, h) do { _Pragma("unroll") for (int m = 0; m < 4; ++m) _Pragma("unroll") for (int k = 0; k < 2; ++k) dst[m][k] = *(const PG8_LAS bf16x8*)(lds + PG8_SA(b, h) + aoff + m * 2048 + k * 1024); } while (0)
; #define PG8_LDB(dst, b, h) do { _Pragma("unroll") for (int n = 0; n < 2; ++n) _Pragma("unroll") for (int k = 0; k < 2; ++k) dst[n][k] = *(const PG8_LAS bf16x8*)(lds + PG8_SB(b, h) + boff + n * 2048 + k * 1024); } while (0)
; #define PG8_MMA(ai, bj, At, Bt) do { __builtin_amdgcn_s_setprio(1); _Pragma("unroll") for (int m = 0; m < 4; ++m) _Pragma("unroll") for (int n = 0; n < 2; ++n) _Pragma("unroll") for (int k = 0; k < 2; ++k) \
;         acc[ai][bj][m][n] = __builtin_amdgcn_mfma_f32_16x16x32_bf16(Bt[n][k], At[m][k], acc[ai][bj][m][n], 0, 0, 0); __builtin_amdgcn_s_setprio(0); } while (0)
; #define PG8_WAIT_V(n) asm volatile("s_waitcnt vmcnt(" #n ")" ::: "memory")
; #define PG8_WAIT_L(n) asm volatile("s_waitcnt lgkmcnt(" #n ")" ::: "memory")
; #define PG8_BAR __builtin_amdgcn_s_barrier()
; #define PG8_SCHED __builtin_amdgcn_sched_barrier(0)
; template <class Epi, class Sched, bool ALIGN_EPI = false, bool SP2 = false>
; __device__ __forceinline__ void gemm_phase(PG8_LAS unsigned char* lds, const Gemm g, const Sched& S, const Epi& E) {
;     ...
;             PG8_WAIT_V(8); PG8_WAIT_L(0); PG8_BAR; PG8_MMA(1, 0, At, B0); PG8_MMA(1, 1, At, B1); PG8_BAR; PG8_SCHED;
;             PG8_LDB(B0, 1, 0); PG8_LDB(B1, 1, 1); PG8_SCHED; PG8_LDA(At, 1, 0); PG8_STAGE(PG8_SA(0, 1), a2 + hstep, voffA);
;             PG8_WAIT_V(8); PG8_WAIT_L(0); PG8_BAR; PG8_MMA(0, 0, At, B0); PG8_MMA(0, 1, At, B1); PG8_BAR; PG8_SCHED;
	s_setprio 1
	s_waitcnt lgkmcnt(0)
	v_mfma_f32_16x16x32_bf16 v[60:63], v[128:131], v[190:193], 0
	v_mfma_f32_16x16x32_bf16 v[56:59], v[160:163], v[190:193], 0
	v_mfma_f32_16x16x32_bf16 v[44:47], v[128:131], v[202:205], 0
	v_mfma_f32_16x16x32_bf16 v[40:43], v[160:163], v[202:205], 0
	v_mfma_f32_16x16x32_bf16 v[28:31], v[128:131], v[210:213], 0
	v_mfma_f32_16x16x32_bf16 v[24:27], v[160:163], v[210:213], 0
	v_mfma_f32_16x16x32_bf16 v[12:15], v[128:131], v[218:221], 0
	v_mfma_f32_16x16x32_bf16 v[8:11], v[160:163], v[218:221], 0
	v_mfma_f32_16x16x32_bf16 v[60:63], v[156:159], v[194:197], v[60:63]
	v_mfma_f32_16x16x32_bf16 v[56:59], v[170:173], v[194:197], v[56:59]
	v_mfma_f32_16x16x32_bf16 v[44:47], v[156:159], v[206:209], v[44:47]
	v_mfma_f32_16x16x32_bf16 v[40:43], v[170:173], v[206:209], v[40:43]
	v_mfma_f32_16x16x32_bf16 v[28:31], v[156:159], v[214:217], v[28:31]
	v_mfma_f32_16x16x32_bf16 v[24:27], v[170:173], v[214:217], v[24:27]
	v_mfma_f32_16x16x32_bf16 v[12:15], v[156:159], v[222:225], v[12:15]
	v_mfma_f32_16x16x32_bf16 v[8:11], v[170:173], v[222:225], v[8:11]
	s_setprio 0
	s_setprio 1
	v_mfma_f32_16x16x32_bf16 v[52:55], v[174:177], v[190:193], 0
	v_mfma_f32_16x16x32_bf16 v[48:51], v[182:185], v[190:193], 0
	v_mfma_f32_16x16x32_bf16 v[36:39], v[174:177], v[202:205], 0
	v_mfma_f32_16x16x32_bf16 v[32:35], v[182:185], v[202:205], 0
	v_mfma_f32_16x16x32_bf16 v[20:23], v[174:177], v[210:213], 0
	v_mfma_f32_16x16x32_bf16 v[16:19], v[182:185], v[210:213], 0
	v_mfma_f32_16x16x32_bf16 v[4:7], v[174:177], v[218:221], 0
	v_mfma_f32_16x16x32_bf16 v[0:3], v[182:185], v[218:221], 0
	v_mfma_f32_16x16x32_bf16 v[52:55], v[178:181], v[194:197], v[52:55]
	v_mfma_f32_16x16x32_bf16 v[48:51], v[186:189], v[194:197], v[48:51]
	v_mfma_f32_16x16x32_bf16 v[36:39], v[178:181], v[206:209], v[36:39]
	v_mfma_f32_16x16x32_bf16 v[32:35], v[186:189], v[206:209], v[32:35]
	v_mfma_f32_16x16x32_bf16 v[20:23], v[178:181], v[214:217], v[20:23]
	v_mfma_f32_16x16x32_bf16 v[16:19], v[186:189], v[214:217], v[16:19]
	v_mfma_f32_16x16x32_bf16 v[4:7], v[178:181], v[222:225], v[4:7]
	v_mfma_f32_16x16x32_bf16 v[0:3], v[186:189], v[222:225], v[0:3]
	s_setprio 0
	s_barrier
	s_add_i32 s16, 0, 0x18000
	v_add_u32_e32 v140, s16, v165
	s_add_i32 s17, 0, 0x1c000
	ds_read_b128 v[128:131], v140
	ds_read_b128 v[156:159], v140 offset:1024
	ds_read_b128 v[160:163], v140 offset:2048
	ds_read_b128 v[170:173], v140 offset:3072
	v_add_u32_e32 v140, s17, v165
	ds_read_b128 v[174:177], v140
	ds_read_b128 v[178:181], v140 offset:1024
	ds_read_b128 v[182:185], v140 offset:2048
	ds_read_b128 v[186:189], v140 offset:3072
	s_mov_b32 m0, s70
	ds_read_b128 v[190:193], v168 offset:32768
	ds_read_b128 v[194:197], v168 offset:33792
	ds_read_b128 v[202:205], v168 offset:34816
	ds_read_b128 v[206:209], v168 offset:35840
	ds_read_b128 v[210:213], v168 offset:36864
	ds_read_b128 v[214:217], v168 offset:37888
	ds_read_b128 v[218:221], v168 offset:38912
	ds_read_b128 v[222:225], v168 offset:39936
	global_load_lds_dwordx4 v226, s[60:61]
	s_mov_b32 m0, s71
	s_nop 0
	global_load_lds_dwordx4 v227, s[60:61]
	s_waitcnt vmcnt(8)
	s_waitcnt lgkmcnt(0)
	s_barrier
	s_setprio 1
	s_waitcnt lgkmcnt(0)
	v_mfma_f32_16x16x32_bf16 v[120:123], v[128:131], v[190:193], v[120:123]
	v_mfma_f32_16x16x32_bf16 v[124:127], v[160:163], v[190:193], v[124:127]
	v_mfma_f32_16x16x32_bf16 v[108:111], v[128:131], v[202:205], v[108:111]
	v_mfma_f32_16x16x32_bf16 v[104:107], v[160:163], v[202:205], v[104:107]
	v_mfma_f32_16x16x32_bf16 v[92:95], v[128:131], v[210:213], v[92:95]
	v_mfma_f32_16x16x32_bf16 v[88:91], v[160:163], v[210:213], v[88:91]
	v_mfma_f32_16x16x32_bf16 v[76:79], v[128:131], v[218:221], v[76:79]
	v_mfma_f32_16x16x32_bf16 v[72:75], v[160:163], v[218:221], v[72:75]
	v_mfma_f32_16x16x32_bf16 v[120:123], v[156:159], v[194:197], v[120:123]
	v_mfma_f32_16x16x32_bf16 v[124:127], v[170:173], v[194:197], v[124:127]
	v_mfma_f32_16x16x32_bf16 v[108:111], v[156:159], v[206:209], v[108:111]
	v_mfma_f32_16x16x32_bf16 v[104:107], v[170:173], v[206:209], v[104:107]
	v_mfma_f32_16x16x32_bf16 v[92:95], v[156:159], v[214:217], v[92:95]
	v_mfma_f32_16x16x32_bf16 v[88:91], v[170:173], v[214:217], v[88:91]
	v_mfma_f32_16x16x32_bf16 v[76:79], v[156:159], v[222:225], v[76:79]
	v_mfma_f32_16x16x32_bf16 v[72:75], v[170:173], v[222:225], v[72:75]
	s_setprio 0
	s_setprio 1
	v_mfma_f32_16x16x32_bf16 v[116:119], v[174:177], v[190:193], v[116:119]
	v_mfma_f32_16x16x32_bf16 v[112:115], v[182:185], v[190:193], v[112:115]
	v_mfma_f32_16x16x32_bf16 v[100:103], v[174:177], v[202:205], v[100:103]
	v_mfma_f32_16x16x32_bf16 v[96:99], v[182:185], v[202:205], v[96:99]
	v_mfma_f32_16x16x32_bf16 v[84:87], v[174:177], v[210:213], v[84:87]
	v_mfma_f32_16x16x32_bf16 v[80:83], v[182:185], v[210:213], v[80:83]
	v_mfma_f32_16x16x32_bf16 v[68:71], v[174:177], v[218:221], v[68:71]
	v_mfma_f32_16x16x32_bf16 v[64:67], v[182:185], v[218:221], v[64:67]
	v_mfma_f32_16x16x32_bf16 v[116:119], v[178:181], v[194:197], v[116:119]
	v_mfma_f32_16x16x32_bf16 v[112:115], v[186:189], v[194:197], v[112:115]
	v_mfma_f32_16x16x32_bf16 v[100:103], v[178:181], v[206:209], v[100:103]
	v_mfma_f32_16x16x32_bf16 v[96:99], v[186:189], v[206:209], v[96:99]
	v_mfma_f32_16x16x32_bf16 v[84:87], v[178:181], v[214:217], v[84:87]
	v_mfma_f32_16x16x32_bf16 v[80:83], v[186:189], v[214:217], v[80:83]
	v_mfma_f32_16x16x32_bf16 v[68:71], v[178:181], v[222:225], v[68:71]
	v_mfma_f32_16x16x32_bf16 v[64:67], v[186:189], v[222:225], v[64:67]
	s_setprio 0
	s_barrier
; #define PG8_STAGE(bufoff, gbase, voff) do { _Pragma("unroll") for (int _i = 0; _i < 2; ++_i) \
;         __builtin_amdgcn_global_load_lds((const unsigned*)((const char*)(gbase) + (voff)[_i]), (PG8_LAS unsigned*)(lds + (bufoff) + ldsw + _i * 8192), 16, 0, 0); } while (0)
; #define PG8_LDA(dst, b, h) do { _Pragma("unroll") for (int m = 0; m < 4; ++m) _Pragma("unroll") for (int k = 0; k < 2; ++k) dst[m][k] = *(const PG8_LAS bf16x8*)(lds + PG8_SA(b, h) + aoff + m * 2048 + k * 1024); } while (0)
; #define PG8_MMA(ai, bj, At, Bt) do { __builtin_amdgcn_s_setprio(1); _Pragma("unroll") for (int m = 0; m < 4; ++m) _Pragma("unroll") for (int n = 0; n < 2; ++n) _Pragma("unroll") for (int k = 0; k < 2; ++k) \
;         acc[ai][bj][m][n] = __builtin_amdgcn_mfma_f32_16x16x32_bf16(Bt[n][k], At[m][k], acc[ai][bj][m][n], 0, 0, 0); __builtin_amdgcn_s_setprio(0); } while (0)
; #define PG8_WAIT_V(n) asm volatile("s_waitcnt vmcnt(" #n ")" ::: "memory")
; #define PG8_WAIT_L(n) asm volatile("s_waitcnt lgkmcnt(" #n ")" ::: "memory")
; #define PG8_BAR __builtin_amdgcn_s_barrier()
; #define PG8_SCHED __builtin_amdgcn_sched_barrier(0)
; template <class Epi, class Sched, bool ALIGN_EPI = false, bool SP2 = false>
; __device__ __forceinline__ void gemm_phase(PG8_LAS unsigned char* lds, const Gemm g, const Sched& S, const Epi& E) {
;     ...
;         for (int t = 0; t < nt; t += 2) {
;             const bool last = (t == nt - 2);
;             const char* a1 = cA + (size_t)(t + 1) * kstep;
;             const char* a2 = last ? nA : cA + (size_t)(t + 2) * kstep; const char* b2 = last ? nB : cB + (size_t)(t + 2) * kstep;
;             const char* a3 = a2 + kstep; const char* b3 = b2 + kstep;
;     ...
;             PG8_LDA(At, 1, 1); PG8_STAGE(PG8_SB(1, 0), b3, voffB); PG8_STAGE(PG8_SB(1, 1), b3 + hstep, voffB); PG8_STAGE(PG8_SA(1, 0), a3, voffA);
;             PG8_WAIT_V(8); PG8_WAIT_L(0); PG8_BAR; PG8_MMA(1, 0, At, B0); PG8_MMA(1, 1, At, B1); PG8_BAR; PG8_SCHED;
	s_add_i32 s16, s16, s49
	s_mov_b32 m0, s16
	ds_read_b128 v[190:193], v168 offset:49152
	ds_read_b128 v[194:197], v168 offset:50176
	ds_read_b128 v[202:205], v168 offset:51200
	ds_read_b128 v[206:209], v168 offset:52224
	ds_read_b128 v[210:213], v168 offset:53248
	ds_read_b128 v[214:217], v168 offset:54272
	ds_read_b128 v[218:221], v168 offset:55296
	ds_read_b128 v[222:225], v168 offset:56320
	global_load_lds_dwordx4 v228, vcc
	s_add_i32 m0, s16, 0x2000
	s_add_i32 s16, s17, s49
	global_load_lds_dwordx4 v229, vcc
	s_mov_b32 m0, s16
	s_nop 0
	global_load_lds_dwordx4 v230, vcc
	s_add_i32 m0, s16, 0x2000
	s_nop 0
	global_load_lds_dwordx4 v231, vcc
	s_mov_b32 m0, s72
	s_nop 0
	global_load_lds_dwordx4 v232, s[60:61]
	s_mov_b32 m0, s73
	s_nop 0
	global_load_lds_dwordx4 v233, s[60:61]
	s_waitcnt vmcnt(8)
	s_waitcnt lgkmcnt(0)
	s_barrier
	s_setprio 1
	s_waitcnt lgkmcnt(0)
	v_mfma_f32_16x16x32_bf16 v[60:63], v[128:131], v[190:193], v[60:63]
	v_mfma_f32_16x16x32_bf16 v[56:59], v[160:163], v[190:193], v[56:59]
	v_mfma_f32_16x16x32_bf16 v[44:47], v[128:131], v[202:205], v[44:47]
	v_mfma_f32_16x16x32_bf16 v[40:43], v[160:163], v[202:205], v[40:43]
	v_mfma_f32_16x16x32_bf16 v[28:31], v[128:131], v[210:213], v[28:31]
	v_mfma_f32_16x16x32_bf16 v[24:27], v[160:163], v[210:213], v[24:27]
	v_mfma_f32_16x16x32_bf16 v[12:15], v[128:131], v[218:221], v[12:15]
	v_mfma_f32_16x16x32_bf16 v[8:11], v[160:163], v[218:221], v[8:11]
	v_mfma_f32_16x16x32_bf16 v[60:63], v[156:159], v[194:197], v[60:63]
	v_mfma_f32_16x16x32_bf16 v[56:59], v[170:173], v[194:197], v[56:59]
	v_mfma_f32_16x16x32_bf16 v[44:47], v[156:159], v[206:209], v[44:47]
	v_mfma_f32_16x16x32_bf16 v[40:43], v[170:173], v[206:209], v[40:43]
	v_mfma_f32_16x16x32_bf16 v[28:31], v[156:159], v[214:217], v[28:31]
	v_mfma_f32_16x16x32_bf16 v[24:27], v[170:173], v[214:217], v[24:27]
	v_mfma_f32_16x16x32_bf16 v[12:15], v[156:159], v[222:225], v[12:15]
	v_mfma_f32_16x16x32_bf16 v[8:11], v[170:173], v[222:225], v[8:11]
	s_setprio 0
	s_setprio 1
	v_mfma_f32_16x16x32_bf16 v[52:55], v[174:177], v[190:193], v[52:55]
	v_mfma_f32_16x16x32_bf16 v[48:51], v[182:185], v[190:193], v[48:51]
	v_mfma_f32_16x16x32_bf16 v[36:39], v[174:177], v[202:205], v[36:39]
	v_mfma_f32_16x16x32_bf16 v[32:35], v[182:185], v[202:205], v[32:35]
	v_mfma_f32_16x16x32_bf16 v[20:23], v[174:177], v[210:213], v[20:23]
	v_mfma_f32_16x16x32_bf16 v[16:19], v[182:185], v[210:213], v[16:19]
	v_mfma_f32_16x16x32_bf16 v[4:7], v[174:177], v[218:221], v[4:7]
	v_mfma_f32_16x16x32_bf16 v[0:3], v[182:185], v[218:221], v[0:3]
	v_mfma_f32_16x16x32_bf16 v[52:55], v[178:181], v[194:197], v[52:55]
	v_mfma_f32_16x16x32_bf16 v[48:51], v[186:189], v[194:197], v[48:51]
	v_mfma_f32_16x16x32_bf16 v[36:39], v[178:181], v[206:209], v[36:39]
	v_mfma_f32_16x16x32_bf16 v[32:35], v[186:189], v[206:209], v[32:35]
	v_mfma_f32_16x16x32_bf16 v[20:23], v[178:181], v[214:217], v[20:23]
	v_mfma_f32_16x16x32_bf16 v[16:19], v[186:189], v[214:217], v[16:19]
	v_mfma_f32_16x16x32_bf16 v[4:7], v[178:181], v[222:225], v[4:7]
	v_mfma_f32_16x16x32_bf16 v[0:3], v[186:189], v[222:225], v[0:3]
	s_setprio 0
	s_barrier
	s_add_u32 s58, s58, 0x100
	s_addc_u32 s59, s59, 0
	s_add_u32 s95, s95, 0x100
	s_addc_u32 s96, s96, 0
	s_cmp_ge_i32 s97, s74
	s_mov_b32 s60, s97
	s_cbranch_scc1 .LBB0_536

;     __device__ bool next(int i, Unit& u) const { if (!so.next(i >> 1, u)) return false; u.sel = i & 1; return true; }
; #define PG8_STAGE(bufoff, gbase, voff) do { _Pragma("unroll") for (int _i = 0; _i < 2; ++_i) \
;         __builtin_amdgcn_global_load_lds((const unsigned*)((const char*)(gbase) + (voff)[_i]), (PG8_LAS unsigned*)(lds + (bufoff) + ldsw + _i * 8192), 16, 0, 0); } while (0)
; #define PG8_LDA(dst, b, h) do { _Pragma("unroll") for (int m = 0; m < 4; ++m) _Pragma("unroll") for (int k = 0; k < 2; ++k) dst[m][k] = *(const PG8_LAS bf16x8*)(lds + PG8_SA(b, h) + aoff + m * 2048 + k * 1024); } while (0)
; #define PG8_LDB(dst, b, h) do { _Pragma("unroll") for (int n = 0; n < 2; ++n) _Pragma("unroll") for (int k = 0; k < 2; ++k) dst[n][k] = *(const PG8_LAS bf16x8*)(lds + PG8_SB(b, h) + boff + n * 2048 + k * 1024); } while (0)
; #define PG8_WAIT_V(n) asm volatile("s_waitcnt vmcnt(" #n ")" ::: "memory")
; #define PG8_BAR __builtin_amdgcn_s_barrier()
; template <class Epi, class Sched, bool ALIGN_EPI = false, bool SP2 = false>
; __device__ __forceinline__ void gemm_phase(PG8_LAS unsigned char* lds, const Gemm g, const Sched& S, const Epi& E) {
;     ...
;         const bool has_next = S.next(ui + 1, nxt);
;         const char* nA = has_next ? (const char*)(nxt.sel ? g.A2 : g.A) + (size_t)nxt.pm * tstep : cA; const char* nB = has_next ? (const char*)(nxt.sel ? g.Bt2 : g.Bt) + (size_t)nxt.pn * tstep : cB;
;         for (int t = 0; t < nt; t += 2) {
;             const bool last = (t == nt - 2);
;             const char* a1 = cA + (size_t)(t + 1) * kstep;
;             const char* a2 = last ? nA : cA + (size_t)(t + 2) * kstep; const char* b2 = last ? nB : cB + (size_t)(t + 2) * kstep;
;             const char* a3 = a2 + kstep; const char* b3 = b2 + kstep;
;             if (last && has_next) S.a_ready(nxt);
;             if constexpr (SP2) {
;             PG8_LDB(B0, 0, 0); PG8_LDB(B1, 0, 1); PG8_SCHED; PG8_LDA(At, 0, 0); PG8_STAGE(PG8_SA(1, 1), a1 + hstep, voffA);
;             PG8_WAIT_V(8); PG8_WAIT_L(0); PG8_BAR; PG8_MMA(0, 0, At, B0); PG8_MMA(0, 1, At, B1); PG8_BAR; PG8_SCHED;
;             PG8_LDA(At, 0, 1); PG8_STAGE(PG8_SB(0, 0), b2, voffB); PG8_STAGE(PG8_SB(0, 1), b2 + hstep, voffB); PG8_STAGE(PG8_SA(0, 0), a2, voffA);
;             PG8_WAIT_V(8); PG8_WAIT_L(0); PG8_BAR; PG8_MMA(1, 0, At, B0); PG8_MMA(1, 1, At, B1); PG8_BAR; PG8_SCHED;
.Lcz_go_728:
	s_add_u32 s6, s6, 0x80
	s_addc_u32 s7, s7, 0
	s_add_u32 s79, s52, 0x100
	s_addc_u32 s80, s53, 0
	s_mov_b32 s52, 0
	v_add_u32_e32 v164, s10, v134
	v_add_u32_e32 v165, s10, v138
	v_add_u32_e32 v218, s10, v132
	v_add_u32_e32 v219, s10, v136
	v_add_u32_e32 v220, 0x80, v134
	v_add_u32_e32 v221, 0x80, v138
	v_add_u32_e32 v222, 0x80, v164
	v_add_u32_e32 v223, 0x80, v165
	v_add_u32_e32 v224, 0x80, v132
	v_add_u32_e32 v225, 0x80, v136
	ds_read_b128 v[128:131], v169
	ds_read_b128 v[148:151], v169 offset:1024
	ds_read_b128 v[152:155], v169 offset:2048
	ds_read_b128 v[156:159], v169 offset:3072
	ds_read_b128 v[160:163], v170
	ds_read_b128 v[172:175], v170 offset:1024
	ds_read_b128 v[176:179], v170 offset:2048
	ds_read_b128 v[180:183], v170 offset:3072
	s_add_i32 s81, s52, 2
	s_add_u32 s16, s6, 0x80
	s_addc_u32 s17, s7, 0
	s_cmp_eq_u32 s69, s52
	s_cselect_b32 s52, s0, s16
	s_cselect_b32 s53, s1, s17
	s_cselect_b32 s83, s51, s80
	s_cselect_b32 s82, s50, s79
	s_add_i32 m0, s56, 0xc000
	ds_read_b128 v[184:187], v171
	ds_read_b128 v[188:191], v171 offset:1024
	ds_read_b128 v[192:195], v171 offset:2048
	ds_read_b128 v[196:199], v171 offset:3072
	ds_read_b128 v[202:205], v171 offset:4096
	ds_read_b128 v[206:209], v171 offset:5120
	ds_read_b128 v[210:213], v171 offset:6144
	ds_read_b128 v[214:217], v171 offset:7168
	global_load_lds_dwordx4 v140, s[6:7]
	s_add_i32 m0, s56, 0xe000
	s_nop 0
	global_load_lds_dwordx4 v142, s[6:7]
	s_waitcnt vmcnt(8)
	s_waitcnt lgkmcnt(0)
	s_barrier
	s_setprio 1
	s_waitcnt lgkmcnt(0)
	v_mfma_f32_16x16x32_bf16 v[120:123], v[128:131], v[184:187], 0
	v_mfma_f32_16x16x32_bf16 v[124:127], v[152:155], v[184:187], 0
	v_mfma_f32_16x16x32_bf16 v[108:111], v[128:131], v[192:195], 0
	v_mfma_f32_16x16x32_bf16 v[104:107], v[152:155], v[192:195], 0
	v_mfma_f32_16x16x32_bf16 v[92:95], v[128:131], v[202:205], 0
	v_mfma_f32_16x16x32_bf16 v[88:91], v[152:155], v[202:205], 0
	v_mfma_f32_16x16x32_bf16 v[76:79], v[128:131], v[210:213], 0
	v_mfma_f32_16x16x32_bf16 v[72:75], v[152:155], v[210:213], 0
	v_mfma_f32_16x16x32_bf16 v[120:123], v[148:151], v[188:191], v[120:123]
	v_mfma_f32_16x16x32_bf16 v[124:127], v[156:159], v[188:191], v[124:127]
	v_mfma_f32_16x16x32_bf16 v[108:111], v[148:151], v[196:199], v[108:111]
	v_mfma_f32_16x16x32_bf16 v[104:107], v[156:159], v[196:199], v[104:107]
	v_mfma_f32_16x16x32_bf16 v[92:95], v[148:151], v[206:209], v[92:95]
	v_mfma_f32_16x16x32_bf16 v[88:91], v[156:159], v[206:209], v[88:91]
	v_mfma_f32_16x16x32_bf16 v[76:79], v[148:151], v[214:217], v[76:79]
	v_mfma_f32_16x16x32_bf16 v[72:75], v[156:159], v[214:217], v[72:75]
	s_setprio 0
	s_setprio 1
	v_mfma_f32_16x16x32_bf16 v[116:119], v[160:163], v[184:187], 0
	v_mfma_f32_16x16x32_bf16 v[112:115], v[176:179], v[184:187], 0
	v_mfma_f32_16x16x32_bf16 v[100:103], v[160:163], v[192:195], 0
	v_mfma_f32_16x16x32_bf16 v[96:99], v[176:179], v[192:195], 0
	v_mfma_f32_16x16x32_bf16 v[84:87], v[160:163], v[202:205], 0
	v_mfma_f32_16x16x32_bf16 v[80:83], v[176:179], v[202:205], 0
	v_mfma_f32_16x16x32_bf16 v[68:71], v[160:163], v[210:213], 0
	v_mfma_f32_16x16x32_bf16 v[64:67], v[176:179], v[210:213], 0
	v_mfma_f32_16x16x32_bf16 v[116:119], v[172:175], v[188:191], v[116:119]
	v_mfma_f32_16x16x32_bf16 v[112:115], v[180:183], v[188:191], v[112:115]
	v_mfma_f32_16x16x32_bf16 v[100:103], v[172:175], v[196:199], v[100:103]
	v_mfma_f32_16x16x32_bf16 v[96:99], v[180:183], v[196:199], v[96:99]
	v_mfma_f32_16x16x32_bf16 v[84:87], v[172:175], v[206:209], v[84:87]
	v_mfma_f32_16x16x32_bf16 v[80:83], v[180:183], v[206:209], v[80:83]
	v_mfma_f32_16x16x32_bf16 v[68:71], v[172:175], v[214:217], v[68:71]
	v_mfma_f32_16x16x32_bf16 v[64:67], v[180:183], v[214:217], v[64:67]
	s_setprio 0
	s_barrier
	s_add_i32 s16, s71, s55
	s_mov_b32 m0, s16
	ds_read_b128 v[184:187], v171 offset:16384
	ds_read_b128 v[188:191], v171 offset:17408
	ds_read_b128 v[192:195], v171 offset:18432
	ds_read_b128 v[196:199], v171 offset:19456
	ds_read_b128 v[202:205], v171 offset:20480
	ds_read_b128 v[206:209], v171 offset:21504
	ds_read_b128 v[210:213], v171 offset:22528
	ds_read_b128 v[214:217], v171 offset:23552
	global_load_lds_dwordx4 v134, s[82:83]
	s_add_i32 m0, s16, 0x2000
	s_add_i32 s16, s72, s55
	global_load_lds_dwordx4 v138, s[82:83]
	s_mov_b32 m0, s16
	s_nop 0
	global_load_lds_dwordx4 v164, s[82:83]
	s_add_i32 m0, s16, 0x2000
	s_nop 0
	global_load_lds_dwordx4 v165, s[82:83]
	s_mov_b32 m0, s56
	s_nop 0
	global_load_lds_dwordx4 v132, s[52:53]
	s_mov_b32 m0, s57
	s_nop 0
	global_load_lds_dwordx4 v136, s[52:53]
	s_waitcnt vmcnt(8)
	s_waitcnt lgkmcnt(0)
	s_barrier
; #define PG8_STAGE(bufoff, gbase, voff) do { _Pragma("unroll") for (int _i = 0; _i < 2; ++_i) \
;         __builtin_amdgcn_global_load_lds((const unsigned*)((const char*)(gbase) + (voff)[_i]), (PG8_LAS unsigned*)(lds + (bufoff) + ldsw + _i * 8192), 16, 0, 0); } while (0)
; #define PG8_LDA(dst, b, h) do { _Pragma("unroll") for (int m = 0; m < 4; ++m) _Pragma("unroll") for (int k = 0; k < 2; ++k) dst[m][k] = *(const PG8_LAS bf16x8*)(lds + PG8_SA(b, h) + aoff + m * 2048 + k * 1024); } while (0)
; #define PG8_LDB(dst, b, h) do { _Pragma("unroll") for (int n = 0; n < 2; ++n) _Pragma("unroll") for (int k = 0; k < 2; ++k) dst[n][k] = *(const PG8_LAS bf16x8*)(lds + PG8_SB(b, h) + boff + n * 2048 + k * 1024); } while (0)
; #define PG8_MMA(ai, bj, At, Bt) do { __builtin_amdgcn_s_setprio(1); _Pragma("unroll") for (int m = 0; m < 4; ++m) _Pragma("unroll") for (int n = 0; n < 2; ++n) _Pragma("unroll") for (int k = 0; k < 2; ++k) \
;         acc[ai][bj][m][n] = __builtin_amdgcn_mfma_f32_16x16x32_bf16(Bt[n][k], At[m][k], acc[ai][bj][m][n], 0, 0, 0); __builtin_amdgcn_s_setprio(0); } while (0)
; #define PG8_WAIT_V(n) asm volatile("s_waitcnt vmcnt(" #n ")" ::: "memory")
; #define PG8_WAIT_L(n) asm volatile("s_waitcnt lgkmcnt(" #n ")" ::: "memory")
; #define PG8_BAR __builtin_amdgcn_s_barrier()
; #define PG8_SCHED __builtin_amdgcn_sched_barrier(0)
; template <class Epi, class Sched, bool ALIGN_EPI = false, bool SP2 = false>
; __device__ __forceinline__ void gemm_phase(PG8_LAS unsigned char* lds, const Gemm g, const Sched& S, const Epi& E) {
;     ...
;             PG8_WAIT_V(8); PG8_WAIT_L(0); PG8_BAR; PG8_MMA(1, 0, At, B0); PG8_MMA(1, 1, At, B1); PG8_BAR; PG8_SCHED;
;             PG8_LDB(B0, 1, 0); PG8_LDB(B1, 1, 1); PG8_SCHED; PG8_LDA(At, 1, 0); PG8_STAGE(PG8_SA(0, 1), a2 + hstep, voffA);
;             PG8_WAIT_V(8); PG8_WAIT_L(0); PG8_BAR; PG8_MMA(0, 0, At, B0); PG8_MMA(0, 1, At, B1); PG8_BAR; PG8_SCHED;
	s_setprio 1
	s_waitcnt lgkmcnt(0)
	v_mfma_f32_16x16x32_bf16 v[60:63], v[128:131], v[184:187], 0
	v_mfma_f32_16x16x32_bf16 v[56:59], v[152:155], v[184:187], 0
	v_mfma_f32_16x16x32_bf16 v[44:47], v[128:131], v[192:195], 0
	v_mfma_f32_16x16x32_bf16 v[40:43], v[152:155], v[192:195], 0
	v_mfma_f32_16x16x32_bf16 v[28:31], v[128:131], v[202:205], 0
	v_mfma_f32_16x16x32_bf16 v[24:27], v[152:155], v[202:205], 0
	v_mfma_f32_16x16x32_bf16 v[12:15], v[128:131], v[210:213], 0
	v_mfma_f32_16x16x32_bf16 v[8:11], v[152:155], v[210:213], 0
	v_mfma_f32_16x16x32_bf16 v[60:63], v[148:151], v[188:191], v[60:63]
	v_mfma_f32_16x16x32_bf16 v[56:59], v[156:159], v[188:191], v[56:59]
	v_mfma_f32_16x16x32_bf16 v[44:47], v[148:151], v[196:199], v[44:47]
	v_mfma_f32_16x16x32_bf16 v[40:43], v[156:159], v[196:199], v[40:43]
	v_mfma_f32_16x16x32_bf16 v[28:31], v[148:151], v[206:209], v[28:31]
	v_mfma_f32_16x16x32_bf16 v[24:27], v[156:159], v[206:209], v[24:27]
	v_mfma_f32_16x16x32_bf16 v[12:15], v[148:151], v[214:217], v[12:15]
	v_mfma_f32_16x16x32_bf16 v[8:11], v[156:159], v[214:217], v[8:11]
	s_setprio 0
	s_setprio 1
	v_mfma_f32_16x16x32_bf16 v[52:55], v[160:163], v[184:187], 0
	v_mfma_f32_16x16x32_bf16 v[48:51], v[176:179], v[184:187], 0
	v_mfma_f32_16x16x32_bf16 v[36:39], v[160:163], v[192:195], 0
	v_mfma_f32_16x16x32_bf16 v[32:35], v[176:179], v[192:195], 0
	v_mfma_f32_16x16x32_bf16 v[20:23], v[160:163], v[202:205], 0
	v_mfma_f32_16x16x32_bf16 v[16:19], v[176:179], v[202:205], 0
	v_mfma_f32_16x16x32_bf16 v[4:7], v[160:163], v[210:213], 0
	v_mfma_f32_16x16x32_bf16 v[0:3], v[176:179], v[210:213], 0
	v_mfma_f32_16x16x32_bf16 v[52:55], v[172:175], v[188:191], v[52:55]
	v_mfma_f32_16x16x32_bf16 v[48:51], v[180:183], v[188:191], v[48:51]
	v_mfma_f32_16x16x32_bf16 v[36:39], v[172:175], v[196:199], v[36:39]
	v_mfma_f32_16x16x32_bf16 v[32:35], v[180:183], v[196:199], v[32:35]
	v_mfma_f32_16x16x32_bf16 v[20:23], v[172:175], v[206:209], v[20:23]
	v_mfma_f32_16x16x32_bf16 v[16:19], v[180:183], v[206:209], v[16:19]
	v_mfma_f32_16x16x32_bf16 v[4:7], v[172:175], v[214:217], v[4:7]
	v_mfma_f32_16x16x32_bf16 v[0:3], v[180:183], v[214:217], v[0:3]
	s_setprio 0
	s_barrier
	s_add_i32 s16, 0, 0x18000
	s_add_i32 s17, 0, 0x1c000
	v_add_u32_e32 v156, s16, v167
	v_add_u32_e32 v180, s17, v167
	ds_read_b128 v[128:131], v156
	ds_read_b128 v[148:151], v156 offset:1024
	ds_read_b128 v[152:155], v156 offset:2048
	ds_read_b128 v[156:159], v156 offset:3072
	ds_read_b128 v[160:163], v180
	ds_read_b128 v[172:175], v180 offset:1024
	ds_read_b128 v[176:179], v180 offset:2048
	ds_read_b128 v[180:183], v180 offset:3072
	s_mov_b32 m0, s58
	ds_read_b128 v[184:187], v171 offset:32768
	ds_read_b128 v[188:191], v171 offset:33792
	ds_read_b128 v[192:195], v171 offset:34816
	ds_read_b128 v[196:199], v171 offset:35840
	ds_read_b128 v[202:205], v171 offset:36864
	ds_read_b128 v[206:209], v171 offset:37888
	ds_read_b128 v[210:213], v171 offset:38912
	ds_read_b128 v[214:217], v171 offset:39936
	global_load_lds_dwordx4 v218, s[52:53]
	s_mov_b32 m0, s59
	s_nop 0
	global_load_lds_dwordx4 v219, s[52:53]
	s_waitcnt vmcnt(8)
	s_waitcnt lgkmcnt(0)
	s_barrier
	s_setprio 1
	s_waitcnt lgkmcnt(0)
	v_mfma_f32_16x16x32_bf16 v[120:123], v[128:131], v[184:187], v[120:123]
	v_mfma_f32_16x16x32_bf16 v[124:127], v[152:155], v[184:187], v[124:127]
	v_mfma_f32_16x16x32_bf16 v[108:111], v[128:131], v[192:195], v[108:111]
	v_mfma_f32_16x16x32_bf16 v[104:107], v[152:155], v[192:195], v[104:107]
	v_mfma_f32_16x16x32_bf16 v[92:95], v[128:131], v[202:205], v[92:95]
	v_mfma_f32_16x16x32_bf16 v[88:91], v[152:155], v[202:205], v[88:91]
	v_mfma_f32_16x16x32_bf16 v[76:79], v[128:131], v[210:213], v[76:79]
	v_mfma_f32_16x16x32_bf16 v[72:75], v[152:155], v[210:213], v[72:75]
	v_mfma_f32_16x16x32_bf16 v[120:123], v[148:151], v[188:191], v[120:123]
	v_mfma_f32_16x16x32_bf16 v[124:127], v[156:159], v[188:191], v[124:127]
	v_mfma_f32_16x16x32_bf16 v[108:111], v[148:151], v[196:199], v[108:111]
	v_mfma_f32_16x16x32_bf16 v[104:107], v[156:159], v[196:199], v[104:107]
	v_mfma_f32_16x16x32_bf16 v[92:95], v[148:151], v[206:209], v[92:95]
	v_mfma_f32_16x16x32_bf16 v[88:91], v[156:159], v[206:209], v[88:91]
	v_mfma_f32_16x16x32_bf16 v[76:79], v[148:151], v[214:217], v[76:79]
	v_mfma_f32_16x16x32_bf16 v[72:75], v[156:159], v[214:217], v[72:75]
	s_setprio 0
	s_setprio 1
	v_mfma_f32_16x16x32_bf16 v[116:119], v[160:163], v[184:187], v[116:119]
	v_mfma_f32_16x16x32_bf16 v[112:115], v[176:179], v[184:187], v[112:115]
	v_mfma_f32_16x16x32_bf16 v[100:103], v[160:163], v[192:195], v[100:103]
	v_mfma_f32_16x16x32_bf16 v[96:99], v[176:179], v[192:195], v[96:99]
	v_mfma_f32_16x16x32_bf16 v[84:87], v[160:163], v[202:205], v[84:87]
	v_mfma_f32_16x16x32_bf16 v[80:83], v[176:179], v[202:205], v[80:83]
	v_mfma_f32_16x16x32_bf16 v[68:71], v[160:163], v[210:213], v[68:71]
	v_mfma_f32_16x16x32_bf16 v[64:67], v[176:179], v[210:213], v[64:67]
	v_mfma_f32_16x16x32_bf16 v[116:119], v[172:175], v[188:191], v[116:119]
	v_mfma_f32_16x16x32_bf16 v[112:115], v[180:183], v[188:191], v[112:115]
	v_mfma_f32_16x16x32_bf16 v[100:103], v[172:175], v[196:199], v[100:103]
	v_mfma_f32_16x16x32_bf16 v[96:99], v[180:183], v[196:199], v[96:99]
	v_mfma_f32_16x16x32_bf16 v[84:87], v[172:175], v[206:209], v[84:87]
	v_mfma_f32_16x16x32_bf16 v[80:83], v[180:183], v[206:209], v[80:83]
	v_mfma_f32_16x16x32_bf16 v[68:71], v[172:175], v[214:217], v[68:71]
	v_mfma_f32_16x16x32_bf16 v[64:67], v[180:183], v[214:217], v[64:67]
	s_setprio 0
	s_barrier
; #define PG8_STAGE(bufoff, gbase, voff) do { _Pragma("unroll") for (int _i = 0; _i < 2; ++_i) \
;         __builtin_amdgcn_global_load_lds((const unsigned*)((const char*)(gbase) + (voff)[_i]), (PG8_LAS unsigned*)(lds + (bufoff) + ldsw + _i * 8192), 16, 0, 0); } while (0)
; #define PG8_LDA(dst, b, h) do { _Pragma("unroll") for (int m = 0; m < 4; ++m) _Pragma("unroll") for (int k = 0; k < 2; ++k) dst[m][k] = *(const PG8_LAS bf16x8*)(lds + PG8_SA(b, h) + aoff + m * 2048 + k * 1024); } while (0)
; #define PG8_MMA(ai, bj, At, Bt) do { __builtin_amdgcn_s_setprio(1); _Pragma("unroll") for (int m = 0; m < 4; ++m) _Pragma("unroll") for (int n = 0; n < 2; ++n) _Pragma("unroll") for (int k = 0; k < 2; ++k) \
;         acc[ai][bj][m][n] = __builtin_amdgcn_mfma_f32_16x16x32_bf16(Bt[n][k], At[m][k], acc[ai][bj][m][n], 0, 0, 0); __builtin_amdgcn_s_setprio(0); } while (0)
; #define PG8_WAIT_V(n) asm volatile("s_waitcnt vmcnt(" #n ")" ::: "memory")
; #define PG8_WAIT_L(n) asm volatile("s_waitcnt lgkmcnt(" #n ")" ::: "memory")
; #define PG8_BAR __builtin_amdgcn_s_barrier()
; #define PG8_SCHED __builtin_amdgcn_sched_barrier(0)
; template <class Epi, class Sched, bool ALIGN_EPI = false, bool SP2 = false>
; __device__ __forceinline__ void gemm_phase(PG8_LAS unsigned char* lds, const Gemm g, const Sched& S, const Epi& E) {
;     ...
;         for (int t = 0; t < nt; t += 2) {
;     ...
;             PG8_LDA(At, 1, 1); PG8_STAGE(PG8_SB(1, 0), b3, voffB); PG8_STAGE(PG8_SB(1, 1), b3 + hstep, voffB); PG8_STAGE(PG8_SA(1, 0), a3, voffA);
;             PG8_WAIT_V(8); PG8_WAIT_L(0); PG8_BAR; PG8_MMA(1, 0, At, B0); PG8_MMA(1, 1, At, B1); PG8_BAR; PG8_SCHED;
	s_add_i32 s16, s16, s55
	s_mov_b32 m0, s16
	ds_read_b128 v[184:187], v171 offset:49152
	ds_read_b128 v[188:191], v171 offset:50176
	ds_read_b128 v[192:195], v171 offset:51200
	ds_read_b128 v[196:199], v171 offset:52224
	ds_read_b128 v[202:205], v171 offset:53248
	ds_read_b128 v[206:209], v171 offset:54272
	ds_read_b128 v[210:213], v171 offset:55296
	ds_read_b128 v[214:217], v171 offset:56320
	global_load_lds_dwordx4 v220, s[82:83]
	s_add_i32 m0, s16, 0x2000
	s_add_i32 s16, s17, s55
	global_load_lds_dwordx4 v221, s[82:83]
	s_mov_b32 m0, s16
	s_nop 0
	global_load_lds_dwordx4 v222, s[82:83]
	s_add_i32 m0, s16, 0x2000
	s_nop 0
	global_load_lds_dwordx4 v223, s[82:83]
	s_mov_b32 m0, s62
	s_nop 0
	global_load_lds_dwordx4 v224, s[52:53]
	s_mov_b32 m0, s63
	s_nop 0
	global_load_lds_dwordx4 v225, s[52:53]
	s_waitcnt vmcnt(8)
	s_waitcnt lgkmcnt(0)
	s_barrier
	s_setprio 1
	s_waitcnt lgkmcnt(0)
	v_mfma_f32_16x16x32_bf16 v[60:63], v[128:131], v[184:187], v[60:63]
	v_mfma_f32_16x16x32_bf16 v[56:59], v[152:155], v[184:187], v[56:59]
	v_mfma_f32_16x16x32_bf16 v[44:47], v[128:131], v[192:195], v[44:47]
	v_mfma_f32_16x16x32_bf16 v[40:43], v[152:155], v[192:195], v[40:43]
	v_mfma_f32_16x16x32_bf16 v[28:31], v[128:131], v[202:205], v[28:31]
	v_mfma_f32_16x16x32_bf16 v[24:27], v[152:155], v[202:205], v[24:27]
	v_mfma_f32_16x16x32_bf16 v[12:15], v[128:131], v[210:213], v[12:15]
	v_mfma_f32_16x16x32_bf16 v[8:11], v[152:155], v[210:213], v[8:11]
	v_mfma_f32_16x16x32_bf16 v[60:63], v[148:151], v[188:191], v[60:63]
	v_mfma_f32_16x16x32_bf16 v[56:59], v[156:159], v[188:191], v[56:59]
	v_mfma_f32_16x16x32_bf16 v[44:47], v[148:151], v[196:199], v[44:47]
	v_mfma_f32_16x16x32_bf16 v[40:43], v[156:159], v[196:199], v[40:43]
	v_mfma_f32_16x16x32_bf16 v[28:31], v[148:151], v[206:209], v[28:31]
	v_mfma_f32_16x16x32_bf16 v[24:27], v[156:159], v[206:209], v[24:27]
	v_mfma_f32_16x16x32_bf16 v[12:15], v[148:151], v[214:217], v[12:15]
	v_mfma_f32_16x16x32_bf16 v[8:11], v[156:159], v[214:217], v[8:11]
	s_setprio 0
	s_setprio 1
	v_mfma_f32_16x16x32_bf16 v[52:55], v[160:163], v[184:187], v[52:55]
	v_mfma_f32_16x16x32_bf16 v[48:51], v[176:179], v[184:187], v[48:51]
	v_mfma_f32_16x16x32_bf16 v[36:39], v[160:163], v[192:195], v[36:39]
	v_mfma_f32_16x16x32_bf16 v[32:35], v[176:179], v[192:195], v[32:35]
	v_mfma_f32_16x16x32_bf16 v[20:23], v[160:163], v[202:205], v[20:23]
	v_mfma_f32_16x16x32_bf16 v[16:19], v[176:179], v[202:205], v[16:19]
	v_mfma_f32_16x16x32_bf16 v[4:7], v[160:163], v[210:213], v[4:7]
	v_mfma_f32_16x16x32_bf16 v[0:3], v[176:179], v[210:213], v[0:3]
	v_mfma_f32_16x16x32_bf16 v[52:55], v[172:175], v[188:191], v[52:55]
	v_mfma_f32_16x16x32_bf16 v[48:51], v[180:183], v[188:191], v[48:51]
	v_mfma_f32_16x16x32_bf16 v[36:39], v[172:175], v[196:199], v[36:39]
	v_mfma_f32_16x16x32_bf16 v[32:35], v[180:183], v[196:199], v[32:35]
	v_mfma_f32_16x16x32_bf16 v[20:23], v[172:175], v[206:209], v[20:23]
	v_mfma_f32_16x16x32_bf16 v[16:19], v[180:183], v[206:209], v[16:19]
	v_mfma_f32_16x16x32_bf16 v[4:7], v[172:175], v[214:217], v[4:7]
	v_mfma_f32_16x16x32_bf16 v[0:3], v[180:183], v[214:217], v[0:3]
	s_setprio 0
	s_barrier
	s_add_u32 s6, s6, 0x100
	s_addc_u32 s7, s7, 0
	s_add_u32 s79, s79, 0x100
	s_addc_u32 s80, s80, 0
	s_cmp_ge_i32 s81, s68
	s_mov_b32 s52, s81
	s_cbranch_scc1 .LBB0_729

;     __device__ bool next(int i, Unit& u) const { if (!so.next(i >> 1, u)) return false; u.sel = i & 1; return true; }
; #define PG8_STAGE(bufoff, gbase, voff) do { _Pragma("unroll") for (int _i = 0; _i < 2; ++_i) \
;         __builtin_amdgcn_global_load_lds((const unsigned*)((const char*)(gbase) + (voff)[_i]), (PG8_LAS unsigned*)(lds + (bufoff) + ldsw + _i * 8192), 16, 0, 0); } while (0)
; #define PG8_LDA(dst, b, h) do { _Pragma("unroll") for (int m = 0; m < 4; ++m) _Pragma("unroll") for (int k = 0; k < 2; ++k) dst[m][k] = *(const PG8_LAS bf16x8*)(lds + PG8_SA(b, h) + aoff + m * 2048 + k * 1024); } while (0)
; #define PG8_LDB(dst, b, h) do { _Pragma("unroll") for (int n = 0; n < 2; ++n) _Pragma("unroll") for (int k = 0; k < 2; ++k) dst[n][k] = *(const PG8_LAS bf16x8*)(lds + PG8_SB(b, h) + boff + n * 2048 + k * 1024); } while (0)
; #define PG8_WAIT_V(n) asm volatile("s_waitcnt vmcnt(" #n ")" ::: "memory")
; #define PG8_BAR __builtin_amdgcn_s_barrier()
; template <class Epi, class Sched, bool ALIGN_EPI = false, bool SP2 = false>
; __device__ __forceinline__ void gemm_phase(PG8_LAS unsigned char* lds, const Gemm g, const Sched& S, const Epi& E) {
;     ...
;         const bool has_next = S.next(ui + 1, nxt);
;         const char* nA = has_next ? (const char*)(nxt.sel ? g.A2 : g.A) + (size_t)nxt.pm * tstep : cA; const char* nB = has_next ? (const char*)(nxt.sel ? g.Bt2 : g.Bt) + (size_t)nxt.pn * tstep : cB;
;         for (int t = 0; t < nt; t += 2) {
;             const bool last = (t == nt - 2);
;             const char* a1 = cA + (size_t)(t + 1) * kstep;
;             const char* a2 = last ? nA : cA + (size_t)(t + 2) * kstep; const char* b2 = last ? nB : cB + (size_t)(t + 2) * kstep;
;             const char* a3 = a2 + kstep; const char* b3 = b2 + kstep;
;             if (last && has_next) S.a_ready(nxt);
;             if constexpr (SP2) {
;             PG8_LDB(B0, 0, 0); PG8_LDB(B1, 0, 1); PG8_SCHED; PG8_LDA(At, 0, 0); PG8_STAGE(PG8_SA(1, 1), a1 + hstep, voffA);
;             PG8_WAIT_V(8); PG8_WAIT_L(0); PG8_BAR; PG8_MMA(0, 0, At, B0); PG8_MMA(0, 1, At, B1); PG8_BAR; PG8_SCHED;
;             PG8_LDA(At, 0, 1); PG8_STAGE(PG8_SB(0, 0), b2, voffB); PG8_STAGE(PG8_SB(0, 1), b2 + hstep, voffB); PG8_STAGE(PG8_SA(0, 0), a2, voffA);
;             PG8_WAIT_V(8); PG8_WAIT_L(0); PG8_BAR; PG8_MMA(1, 0, At, B0); PG8_MMA(1, 1, At, B1); PG8_BAR; PG8_SCHED;
.Lcz_go_875:
	s_add_u32 s50, s50, 0x80
	s_addc_u32 s51, s51, 0
	s_add_u32 s78, s52, 0x100
	s_addc_u32 s79, s53, 0
	s_mov_b32 s52, 0
	v_add_u32_e32 v218, s12, v130
	v_add_u32_e32 v219, s12, v134
	v_add_u32_e32 v220, s12, v128
	v_add_u32_e32 v221, s12, v132
	v_add_u32_e32 v222, 0x80, v130
	v_add_u32_e32 v223, 0x80, v134
	v_add_u32_e32 v224, 0x80, v218
	v_add_u32_e32 v225, 0x80, v219
	v_add_u32_e32 v226, 0x80, v128
	v_add_u32_e32 v227, 0x80, v132
	ds_read_b128 v[144:147], v151
	ds_read_b128 v[156:159], v151 offset:1024
	ds_read_b128 v[160:163], v151 offset:2048
	ds_read_b128 v[164:167], v151 offset:3072
	ds_read_b128 v[168:171], v152
	ds_read_b128 v[172:175], v152 offset:1024
	ds_read_b128 v[176:179], v152 offset:2048
	ds_read_b128 v[180:183], v152 offset:3072
	s_add_i32 s80, s52, 2
	s_add_u32 s16, s50, 0x80
	s_addc_u32 s17, s51, 0
	s_cmp_eq_u32 s68, s52
	s_cselect_b32 s52, s0, s16
	s_cselect_b32 s53, s1, s17
	s_cselect_b32 s83, s49, s79
	s_cselect_b32 s82, s48, s78
	s_add_i32 m0, s56, 0xc000
	ds_read_b128 v[184:187], v153
	ds_read_b128 v[188:191], v153 offset:1024
	ds_read_b128 v[192:195], v153 offset:2048
	ds_read_b128 v[196:199], v153 offset:3072
	ds_read_b128 v[202:205], v153 offset:4096
	ds_read_b128 v[206:209], v153 offset:5120
	ds_read_b128 v[210:213], v153 offset:6144
	ds_read_b128 v[214:217], v153 offset:7168
	global_load_lds_dwordx4 v136, s[50:51]
	s_add_i32 m0, s56, 0xe000
	s_nop 0
	global_load_lds_dwordx4 v138, s[50:51]
	s_waitcnt vmcnt(8)
	s_waitcnt lgkmcnt(0)
	s_barrier
	s_setprio 1
	s_waitcnt lgkmcnt(0)
	v_mfma_f32_16x16x32_bf16 v[124:127], v[144:147], v[184:187], 0
	v_mfma_f32_16x16x32_bf16 v[120:123], v[160:163], v[184:187], 0
	v_mfma_f32_16x16x32_bf16 v[108:111], v[144:147], v[192:195], 0
	v_mfma_f32_16x16x32_bf16 v[104:107], v[160:163], v[192:195], 0
	v_mfma_f32_16x16x32_bf16 v[92:95], v[144:147], v[202:205], 0
	v_mfma_f32_16x16x32_bf16 v[88:91], v[160:163], v[202:205], 0
	v_mfma_f32_16x16x32_bf16 v[76:79], v[144:147], v[210:213], 0
	v_mfma_f32_16x16x32_bf16 v[72:75], v[160:163], v[210:213], 0
	v_mfma_f32_16x16x32_bf16 v[124:127], v[156:159], v[188:191], v[124:127]
	v_mfma_f32_16x16x32_bf16 v[120:123], v[164:167], v[188:191], v[120:123]
	v_mfma_f32_16x16x32_bf16 v[108:111], v[156:159], v[196:199], v[108:111]
	v_mfma_f32_16x16x32_bf16 v[104:107], v[164:167], v[196:199], v[104:107]
	v_mfma_f32_16x16x32_bf16 v[92:95], v[156:159], v[206:209], v[92:95]
	v_mfma_f32_16x16x32_bf16 v[88:91], v[164:167], v[206:209], v[88:91]
	v_mfma_f32_16x16x32_bf16 v[76:79], v[156:159], v[214:217], v[76:79]
	v_mfma_f32_16x16x32_bf16 v[72:75], v[164:167], v[214:217], v[72:75]
	s_setprio 0
	s_setprio 1
	v_mfma_f32_16x16x32_bf16 v[116:119], v[168:171], v[184:187], 0
	v_mfma_f32_16x16x32_bf16 v[112:115], v[176:179], v[184:187], 0
	v_mfma_f32_16x16x32_bf16 v[100:103], v[168:171], v[192:195], 0
	v_mfma_f32_16x16x32_bf16 v[96:99], v[176:179], v[192:195], 0
	v_mfma_f32_16x16x32_bf16 v[84:87], v[168:171], v[202:205], 0
	v_mfma_f32_16x16x32_bf16 v[80:83], v[176:179], v[202:205], 0
	v_mfma_f32_16x16x32_bf16 v[68:71], v[168:171], v[210:213], 0
	v_mfma_f32_16x16x32_bf16 v[64:67], v[176:179], v[210:213], 0
	v_mfma_f32_16x16x32_bf16 v[116:119], v[172:175], v[188:191], v[116:119]
	v_mfma_f32_16x16x32_bf16 v[112:115], v[180:183], v[188:191], v[112:115]
	v_mfma_f32_16x16x32_bf16 v[100:103], v[172:175], v[196:199], v[100:103]
	v_mfma_f32_16x16x32_bf16 v[96:99], v[180:183], v[196:199], v[96:99]
	v_mfma_f32_16x16x32_bf16 v[84:87], v[172:175], v[206:209], v[84:87]
	v_mfma_f32_16x16x32_bf16 v[80:83], v[180:183], v[206:209], v[80:83]
	v_mfma_f32_16x16x32_bf16 v[68:71], v[172:175], v[214:217], v[68:71]
	v_mfma_f32_16x16x32_bf16 v[64:67], v[180:183], v[214:217], v[64:67]
	s_setprio 0
	s_barrier
	s_add_i32 s16, s72, s55
	s_mov_b32 m0, s16
	ds_read_b128 v[184:187], v153 offset:16384
	ds_read_b128 v[188:191], v153 offset:17408
	ds_read_b128 v[192:195], v153 offset:18432
	ds_read_b128 v[196:199], v153 offset:19456
	ds_read_b128 v[202:205], v153 offset:20480
	ds_read_b128 v[206:209], v153 offset:21504
	ds_read_b128 v[210:213], v153 offset:22528
	ds_read_b128 v[214:217], v153 offset:23552
	global_load_lds_dwordx4 v130, s[82:83]
	s_add_i32 m0, s16, 0x2000
	s_add_i32 s16, s73, s55
	global_load_lds_dwordx4 v134, s[82:83]
	s_mov_b32 m0, s16
	s_nop 0
	global_load_lds_dwordx4 v218, s[82:83]
	s_add_i32 m0, s16, 0x2000
	s_nop 0
	global_load_lds_dwordx4 v219, s[82:83]
	s_mov_b32 m0, s56
	s_nop 0
	global_load_lds_dwordx4 v128, s[52:53]
	s_mov_b32 m0, s57
	s_nop 0
	global_load_lds_dwordx4 v132, s[52:53]
	s_waitcnt vmcnt(8)
	s_waitcnt lgkmcnt(0)
	s_barrier
; #define PG8_STAGE(bufoff, gbase, voff) do { _Pragma("unroll") for (int _i = 0; _i < 2; ++_i) \
;         __builtin_amdgcn_global_load_lds((const unsigned*)((const char*)(gbase) + (voff)[_i]), (PG8_LAS unsigned*)(lds + (bufoff) + ldsw + _i * 8192), 16, 0, 0); } while (0)
; #define PG8_LDA(dst, b, h) do { _Pragma("unroll") for (int m = 0; m < 4; ++m) _Pragma("unroll") for (int k = 0; k < 2; ++k) dst[m][k] = *(const PG8_LAS bf16x8*)(lds + PG8_SA(b, h) + aoff + m * 2048 + k * 1024); } while (0)
; #define PG8_LDB(dst, b, h) do { _Pragma("unroll") for (int n = 0; n < 2; ++n) _Pragma("unroll") for (int k = 0; k < 2; ++k) dst[n][k] = *(const PG8_LAS bf16x8*)(lds + PG8_SB(b, h) + boff + n * 2048 + k * 1024); } while (0)
; #define PG8_MMA(ai, bj, At, Bt) do { __builtin_amdgcn_s_setprio(1); _Pragma("unroll") for (int m = 0; m < 4; ++m) _Pragma("unroll") for (int n = 0; n < 2; ++n) _Pragma("unroll") for (int k = 0; k < 2; ++k) \
;         acc[ai][bj][m][n] = __builtin_amdgcn_mfma_f32_16x16x32_bf16(Bt[n][k], At[m][k], acc[ai][bj][m][n], 0, 0, 0); __builtin_amdgcn_s_setprio(0); } while (0)
; #define PG8_WAIT_V(n) asm volatile("s_waitcnt vmcnt(" #n ")" ::: "memory")
; #define PG8_WAIT_L(n) asm volatile("s_waitcnt lgkmcnt(" #n ")" ::: "memory")
; #define PG8_BAR __builtin_amdgcn_s_barrier()
; #define PG8_SCHED __builtin_amdgcn_sched_barrier(0)
; template <class Epi, class Sched, bool ALIGN_EPI = false, bool SP2 = false>
; __device__ __forceinline__ void gemm_phase(PG8_LAS unsigned char* lds, const Gemm g, const Sched& S, const Epi& E) {
;     ...
;             PG8_WAIT_V(8); PG8_WAIT_L(0); PG8_BAR; PG8_MMA(1, 0, At, B0); PG8_MMA(1, 1, At, B1); PG8_BAR; PG8_SCHED;
;             PG8_LDB(B0, 1, 0); PG8_LDB(B1, 1, 1); PG8_SCHED; PG8_LDA(At, 1, 0); PG8_STAGE(PG8_SA(0, 1), a2 + hstep, voffA);
;             PG8_WAIT_V(8); PG8_WAIT_L(0); PG8_BAR; PG8_MMA(0, 0, At, B0); PG8_MMA(0, 1, At, B1); PG8_BAR; PG8_SCHED;
	s_setprio 1
	s_waitcnt lgkmcnt(0)
	v_mfma_f32_16x16x32_bf16 v[60:63], v[144:147], v[184:187], 0
	v_mfma_f32_16x16x32_bf16 v[56:59], v[160:163], v[184:187], 0
	v_mfma_f32_16x16x32_bf16 v[44:47], v[144:147], v[192:195], 0
	v_mfma_f32_16x16x32_bf16 v[40:43], v[160:163], v[192:195], 0
	v_mfma_f32_16x16x32_bf16 v[28:31], v[144:147], v[202:205], 0
	v_mfma_f32_16x16x32_bf16 v[24:27], v[160:163], v[202:205], 0
	v_mfma_f32_16x16x32_bf16 v[12:15], v[144:147], v[210:213], 0
	v_mfma_f32_16x16x32_bf16 v[8:11], v[160:163], v[210:213], 0
	v_mfma_f32_16x16x32_bf16 v[60:63], v[156:159], v[188:191], v[60:63]
	v_mfma_f32_16x16x32_bf16 v[56:59], v[164:167], v[188:191], v[56:59]
	v_mfma_f32_16x16x32_bf16 v[44:47], v[156:159], v[196:199], v[44:47]
	v_mfma_f32_16x16x32_bf16 v[40:43], v[164:167], v[196:199], v[40:43]
	v_mfma_f32_16x16x32_bf16 v[28:31], v[156:159], v[206:209], v[28:31]
	v_mfma_f32_16x16x32_bf16 v[24:27], v[164:167], v[206:209], v[24:27]
	v_mfma_f32_16x16x32_bf16 v[12:15], v[156:159], v[214:217], v[12:15]
	v_mfma_f32_16x16x32_bf16 v[8:11], v[164:167], v[214:217], v[8:11]
	s_setprio 0
	s_setprio 1
	v_mfma_f32_16x16x32_bf16 v[52:55], v[168:171], v[184:187], 0
	v_mfma_f32_16x16x32_bf16 v[48:51], v[176:179], v[184:187], 0
	v_mfma_f32_16x16x32_bf16 v[36:39], v[168:171], v[192:195], 0
	v_mfma_f32_16x16x32_bf16 v[32:35], v[176:179], v[192:195], 0
	v_mfma_f32_16x16x32_bf16 v[20:23], v[168:171], v[202:205], 0
	v_mfma_f32_16x16x32_bf16 v[16:19], v[176:179], v[202:205], 0
	v_mfma_f32_16x16x32_bf16 v[4:7], v[168:171], v[210:213], 0
	v_mfma_f32_16x16x32_bf16 v[0:3], v[176:179], v[210:213], 0
	v_mfma_f32_16x16x32_bf16 v[52:55], v[172:175], v[188:191], v[52:55]
	v_mfma_f32_16x16x32_bf16 v[48:51], v[180:183], v[188:191], v[48:51]
	v_mfma_f32_16x16x32_bf16 v[36:39], v[172:175], v[196:199], v[36:39]
	v_mfma_f32_16x16x32_bf16 v[32:35], v[180:183], v[196:199], v[32:35]
	v_mfma_f32_16x16x32_bf16 v[20:23], v[172:175], v[206:209], v[20:23]
	v_mfma_f32_16x16x32_bf16 v[16:19], v[180:183], v[206:209], v[16:19]
	v_mfma_f32_16x16x32_bf16 v[4:7], v[172:175], v[214:217], v[4:7]
	v_mfma_f32_16x16x32_bf16 v[0:3], v[180:183], v[214:217], v[0:3]
	s_setprio 0
	s_barrier
	s_add_i32 s16, 0, 0x18000
	v_add_u32_e32 v155, s16, v149
	s_add_i32 s17, 0, 0x1c000
	ds_read_b128 v[144:147], v155
	ds_read_b128 v[156:159], v155 offset:1024
	ds_read_b128 v[160:163], v155 offset:2048
	ds_read_b128 v[164:167], v155 offset:3072
	v_add_u32_e32 v155, s17, v149
	ds_read_b128 v[168:171], v155
	ds_read_b128 v[172:175], v155 offset:1024
	ds_read_b128 v[176:179], v155 offset:2048
	ds_read_b128 v[180:183], v155 offset:3072
	s_mov_b32 m0, s58
	ds_read_b128 v[184:187], v153 offset:32768
	ds_read_b128 v[188:191], v153 offset:33792
	ds_read_b128 v[192:195], v153 offset:34816
	ds_read_b128 v[196:199], v153 offset:35840
	ds_read_b128 v[202:205], v153 offset:36864
	ds_read_b128 v[206:209], v153 offset:37888
	ds_read_b128 v[210:213], v153 offset:38912
	ds_read_b128 v[214:217], v153 offset:39936
	global_load_lds_dwordx4 v220, s[52:53]
	s_mov_b32 m0, s59
	s_nop 0
	global_load_lds_dwordx4 v221, s[52:53]
	s_waitcnt vmcnt(8)
	s_waitcnt lgkmcnt(0)
	s_barrier
	s_setprio 1
	s_waitcnt lgkmcnt(0)
	v_mfma_f32_16x16x32_bf16 v[124:127], v[144:147], v[184:187], v[124:127]
	v_mfma_f32_16x16x32_bf16 v[120:123], v[160:163], v[184:187], v[120:123]
	v_mfma_f32_16x16x32_bf16 v[108:111], v[144:147], v[192:195], v[108:111]
	v_mfma_f32_16x16x32_bf16 v[104:107], v[160:163], v[192:195], v[104:107]
	v_mfma_f32_16x16x32_bf16 v[92:95], v[144:147], v[202:205], v[92:95]
	v_mfma_f32_16x16x32_bf16 v[88:91], v[160:163], v[202:205], v[88:91]
	v_mfma_f32_16x16x32_bf16 v[76:79], v[144:147], v[210:213], v[76:79]
	v_mfma_f32_16x16x32_bf16 v[72:75], v[160:163], v[210:213], v[72:75]
	v_mfma_f32_16x16x32_bf16 v[124:127], v[156:159], v[188:191], v[124:127]
	v_mfma_f32_16x16x32_bf16 v[120:123], v[164:167], v[188:191], v[120:123]
	v_mfma_f32_16x16x32_bf16 v[108:111], v[156:159], v[196:199], v[108:111]
	v_mfma_f32_16x16x32_bf16 v[104:107], v[164:167], v[196:199], v[104:107]
	v_mfma_f32_16x16x32_bf16 v[92:95], v[156:159], v[206:209], v[92:95]
	v_mfma_f32_16x16x32_bf16 v[88:91], v[164:167], v[206:209], v[88:91]
	v_mfma_f32_16x16x32_bf16 v[76:79], v[156:159], v[214:217], v[76:79]
	v_mfma_f32_16x16x32_bf16 v[72:75], v[164:167], v[214:217], v[72:75]
	s_setprio 0
	s_setprio 1
	v_mfma_f32_16x16x32_bf16 v[116:119], v[168:171], v[184:187], v[116:119]
	v_mfma_f32_16x16x32_bf16 v[112:115], v[176:179], v[184:187], v[112:115]
	v_mfma_f32_16x16x32_bf16 v[100:103], v[168:171], v[192:195], v[100:103]
	v_mfma_f32_16x16x32_bf16 v[96:99], v[176:179], v[192:195], v[96:99]
	v_mfma_f32_16x16x32_bf16 v[84:87], v[168:171], v[202:205], v[84:87]
	v_mfma_f32_16x16x32_bf16 v[80:83], v[176:179], v[202:205], v[80:83]
	v_mfma_f32_16x16x32_bf16 v[68:71], v[168:171], v[210:213], v[68:71]
	v_mfma_f32_16x16x32_bf16 v[64:67], v[176:179], v[210:213], v[64:67]
	v_mfma_f32_16x16x32_bf16 v[116:119], v[172:175], v[188:191], v[116:119]
	v_mfma_f32_16x16x32_bf16 v[112:115], v[180:183], v[188:191], v[112:115]
	v_mfma_f32_16x16x32_bf16 v[100:103], v[172:175], v[196:199], v[100:103]
	v_mfma_f32_16x16x32_bf16 v[96:99], v[180:183], v[196:199], v[96:99]
	v_mfma_f32_16x16x32_bf16 v[84:87], v[172:175], v[206:209], v[84:87]
	v_mfma_f32_16x16x32_bf16 v[80:83], v[180:183], v[206:209], v[80:83]
	v_mfma_f32_16x16x32_bf16 v[68:71], v[172:175], v[214:217], v[68:71]
	v_mfma_f32_16x16x32_bf16 v[64:67], v[180:183], v[214:217], v[64:67]
	s_setprio 0
	s_barrier
; #define PG8_STAGE(bufoff, gbase, voff) do { _Pragma("unroll") for (int _i = 0; _i < 2; ++_i) \
;         __builtin_amdgcn_global_load_lds((const unsigned*)((const char*)(gbase) + (voff)[_i]), (PG8_LAS unsigned*)(lds + (bufoff) + ldsw + _i * 8192), 16, 0, 0); } while (0)
; #define PG8_LDA(dst, b, h) do { _Pragma("unroll") for (int m = 0; m < 4; ++m) _Pragma("unroll") for (int k = 0; k < 2; ++k) dst[m][k] = *(const PG8_LAS bf16x8*)(lds + PG8_SA(b, h) + aoff + m * 2048 + k * 1024); } while (0)
; #define PG8_MMA(ai, bj, At, Bt) do { __builtin_amdgcn_s_setprio(1); _Pragma("unroll") for (int m = 0; m < 4; ++m) _Pragma("unroll") for (int n = 0; n < 2; ++n) _Pragma("unroll") for (int k = 0; k < 2; ++k) \
;         acc[ai][bj][m][n] = __builtin_amdgcn_mfma_f32_16x16x32_bf16(Bt[n][k], At[m][k], acc[ai][bj][m][n], 0, 0, 0); __builtin_amdgcn_s_setprio(0); } while (0)
; #define PG8_WAIT_V(n) asm volatile("s_waitcnt vmcnt(" #n ")" ::: "memory")
; #define PG8_WAIT_L(n) asm volatile("s_waitcnt lgkmcnt(" #n ")" ::: "memory")
; #define PG8_BAR __builtin_amdgcn_s_barrier()
; #define PG8_SCHED __builtin_amdgcn_sched_barrier(0)
; template <class Epi, class Sched, bool ALIGN_EPI = false, bool SP2 = false>
; __device__ __forceinline__ void gemm_phase(PG8_LAS unsigned char* lds, const Gemm g, const Sched& S, const Epi& E) {
;     ...
;         for (int t = 0; t < nt; t += 2) {
;     ...
;             PG8_LDA(At, 1, 1); PG8_STAGE(PG8_SB(1, 0), b3, voffB); PG8_STAGE(PG8_SB(1, 1), b3 + hstep, voffB); PG8_STAGE(PG8_SA(1, 0), a3, voffA);
;             PG8_WAIT_V(8); PG8_WAIT_L(0); PG8_BAR; PG8_MMA(1, 0, At, B0); PG8_MMA(1, 1, At, B1); PG8_BAR; PG8_SCHED;
	s_add_i32 s16, s16, s55
	s_mov_b32 m0, s16
	ds_read_b128 v[184:187], v153 offset:49152
	ds_read_b128 v[188:191], v153 offset:50176
	ds_read_b128 v[192:195], v153 offset:51200
	ds_read_b128 v[196:199], v153 offset:52224
	ds_read_b128 v[202:205], v153 offset:53248
	ds_read_b128 v[206:209], v153 offset:54272
	ds_read_b128 v[210:213], v153 offset:55296
	ds_read_b128 v[214:217], v153 offset:56320
	global_load_lds_dwordx4 v222, s[82:83]
	s_add_i32 m0, s16, 0x2000
	s_add_i32 s16, s17, s55
	global_load_lds_dwordx4 v223, s[82:83]
	s_mov_b32 m0, s16
	s_nop 0
	global_load_lds_dwordx4 v224, s[82:83]
	s_add_i32 m0, s16, 0x2000
	s_nop 0
	global_load_lds_dwordx4 v225, s[82:83]
	s_mov_b32 m0, s60
	s_nop 0
	global_load_lds_dwordx4 v226, s[52:53]
	s_mov_b32 m0, s61
	s_nop 0
	global_load_lds_dwordx4 v227, s[52:53]
	s_waitcnt vmcnt(8)
	s_waitcnt lgkmcnt(0)
	s_barrier
	s_setprio 1
	s_waitcnt lgkmcnt(0)
	v_mfma_f32_16x16x32_bf16 v[60:63], v[144:147], v[184:187], v[60:63]
	v_mfma_f32_16x16x32_bf16 v[56:59], v[160:163], v[184:187], v[56:59]
	v_mfma_f32_16x16x32_bf16 v[44:47], v[144:147], v[192:195], v[44:47]
	v_mfma_f32_16x16x32_bf16 v[40:43], v[160:163], v[192:195], v[40:43]
	v_mfma_f32_16x16x32_bf16 v[28:31], v[144:147], v[202:205], v[28:31]
	v_mfma_f32_16x16x32_bf16 v[24:27], v[160:163], v[202:205], v[24:27]
	v_mfma_f32_16x16x32_bf16 v[12:15], v[144:147], v[210:213], v[12:15]
	v_mfma_f32_16x16x32_bf16 v[8:11], v[160:163], v[210:213], v[8:11]
	v_mfma_f32_16x16x32_bf16 v[60:63], v[156:159], v[188:191], v[60:63]
	v_mfma_f32_16x16x32_bf16 v[56:59], v[164:167], v[188:191], v[56:59]
	v_mfma_f32_16x16x32_bf16 v[44:47], v[156:159], v[196:199], v[44:47]
	v_mfma_f32_16x16x32_bf16 v[40:43], v[164:167], v[196:199], v[40:43]
	v_mfma_f32_16x16x32_bf16 v[28:31], v[156:159], v[206:209], v[28:31]
	v_mfma_f32_16x16x32_bf16 v[24:27], v[164:167], v[206:209], v[24:27]
	v_mfma_f32_16x16x32_bf16 v[12:15], v[156:159], v[214:217], v[12:15]
	v_mfma_f32_16x16x32_bf16 v[8:11], v[164:167], v[214:217], v[8:11]
	s_setprio 0
	s_setprio 1
	v_mfma_f32_16x16x32_bf16 v[52:55], v[168:171], v[184:187], v[52:55]
	v_mfma_f32_16x16x32_bf16 v[48:51], v[176:179], v[184:187], v[48:51]
	v_mfma_f32_16x16x32_bf16 v[36:39], v[168:171], v[192:195], v[36:39]
	v_mfma_f32_16x16x32_bf16 v[32:35], v[176:179], v[192:195], v[32:35]
	v_mfma_f32_16x16x32_bf16 v[20:23], v[168:171], v[202:205], v[20:23]
	v_mfma_f32_16x16x32_bf16 v[16:19], v[176:179], v[202:205], v[16:19]
	v_mfma_f32_16x16x32_bf16 v[4:7], v[168:171], v[210:213], v[4:7]
	v_mfma_f32_16x16x32_bf16 v[0:3], v[176:179], v[210:213], v[0:3]
	v_mfma_f32_16x16x32_bf16 v[52:55], v[172:175], v[188:191], v[52:55]
	v_mfma_f32_16x16x32_bf16 v[48:51], v[180:183], v[188:191], v[48:51]
	v_mfma_f32_16x16x32_bf16 v[36:39], v[172:175], v[196:199], v[36:39]
	v_mfma_f32_16x16x32_bf16 v[32:35], v[180:183], v[196:199], v[32:35]
	v_mfma_f32_16x16x32_bf16 v[20:23], v[172:175], v[206:209], v[20:23]
	v_mfma_f32_16x16x32_bf16 v[16:19], v[180:183], v[206:209], v[16:19]
	v_mfma_f32_16x16x32_bf16 v[4:7], v[172:175], v[214:217], v[4:7]
	v_mfma_f32_16x16x32_bf16 v[0:3], v[180:183], v[214:217], v[0:3]
	s_setprio 0
	s_barrier
	s_add_u32 s50, s50, 0x100
	s_addc_u32 s51, s51, 0
	s_add_u32 s78, s78, 0x100
	s_addc_u32 s79, s79, 0
	s_cmp_ge_i32 s80, s63
	s_mov_b32 s52, s80
	s_cbranch_scc1 .LBB0_876

;     __device__ bool next(int i, Unit& u) const { if (!so.next(i >> 1, u)) return false; u.sel = i & 1; return true; }
; #define PG8_STAGE(bufoff, gbase, voff) do { _Pragma("unroll") for (int _i = 0; _i < 2; ++_i) \
;         __builtin_amdgcn_global_load_lds((const unsigned*)((const char*)(gbase) + (voff)[_i]), (PG8_LAS unsigned*)(lds + (bufoff) + ldsw + _i * 8192), 16, 0, 0); } while (0)
; #define PG8_LDA(dst, b, h) do { _Pragma("unroll") for (int m = 0; m < 4; ++m) _Pragma("unroll") for (int k = 0; k < 2; ++k) dst[m][k] = *(const PG8_LAS bf16x8*)(lds + PG8_SA(b, h) + aoff + m * 2048 + k * 1024); } while (0)
; #define PG8_LDB(dst, b, h) do { _Pragma("unroll") for (int n = 0; n < 2; ++n) _Pragma("unroll") for (int k = 0; k < 2; ++k) dst[n][k] = *(const PG8_LAS bf16x8*)(lds + PG8_SB(b, h) + boff + n * 2048 + k * 1024); } while (0)
; #define PG8_WAIT_V(n) asm volatile("s_waitcnt vmcnt(" #n ")" ::: "memory")
; #define PG8_BAR __builtin_amdgcn_s_barrier()
; template <class Epi, class Sched, bool ALIGN_EPI = false, bool SP2 = false>
; __device__ __forceinline__ void gemm_phase(PG8_LAS unsigned char* lds, const Gemm g, const Sched& S, const Epi& E) {
;     ...
;         const bool has_next = S.next(ui + 1, nxt);
;         const char* nA = has_next ? (const char*)(nxt.sel ? g.A2 : g.A) + (size_t)nxt.pm * tstep : cA; const char* nB = has_next ? (const char*)(nxt.sel ? g.Bt2 : g.Bt) + (size_t)nxt.pn * tstep : cB;
;         for (int t = 0; t < nt; t += 2) {
;             const bool last = (t == nt - 2);
;             const char* a1 = cA + (size_t)(t + 1) * kstep;
;             const char* a2 = last ? nA : cA + (size_t)(t + 2) * kstep; const char* b2 = last ? nB : cB + (size_t)(t + 2) * kstep;
;             const char* a3 = a2 + kstep; const char* b3 = b2 + kstep;
;             if (last && has_next) S.a_ready(nxt);
;             if constexpr (SP2) {
;             PG8_LDB(B0, 0, 0); PG8_LDB(B1, 0, 1); PG8_SCHED; PG8_LDA(At, 0, 0); PG8_STAGE(PG8_SA(1, 1), a1 + hstep, voffA);
;             PG8_WAIT_V(8); PG8_WAIT_L(0); PG8_BAR; PG8_MMA(0, 0, At, B0); PG8_MMA(0, 1, At, B1); PG8_BAR; PG8_SCHED;
;             PG8_LDA(At, 0, 1); PG8_STAGE(PG8_SB(0, 0), b2, voffB); PG8_STAGE(PG8_SB(0, 1), b2 + hstep, voffB); PG8_STAGE(PG8_SA(0, 0), a2, voffA);
;             PG8_WAIT_V(8); PG8_WAIT_L(0); PG8_BAR; PG8_MMA(1, 0, At, B0); PG8_MMA(1, 1, At, B1); PG8_BAR; PG8_SCHED;
.Lcz_go_1021:
	s_add_u32 s42, s42, 0x80
	s_addc_u32 s43, s43, 0
	s_add_u32 s68, s44, 0x100
	s_addc_u32 s69, s45, 0
	s_mov_b32 s44, 0
	v_add_u32_e32 v198, s10, v132
	v_add_u32_e32 v199, s10, v128
	v_add_u32_e32 v218, s10, v134
	v_add_u32_e32 v219, s10, v130
	v_add_u32_e32 v220, 0x80, v132
	v_add_u32_e32 v221, 0x80, v128
	v_add_u32_e32 v222, 0x80, v198
	v_add_u32_e32 v223, 0x80, v199
	v_add_u32_e32 v224, 0x80, v134
	v_add_u32_e32 v225, 0x80, v130
	ds_read_b128 v[150:153], v147
	ds_read_b128 v[154:157], v147 offset:1024
	ds_read_b128 v[158:161], v147 offset:2048
	ds_read_b128 v[162:165], v147 offset:3072
	ds_read_b128 v[166:169], v148
	ds_read_b128 v[170:173], v148 offset:1024
	ds_read_b128 v[174:177], v148 offset:2048
	ds_read_b128 v[178:181], v148 offset:3072
	s_add_i32 s70, s44, 2
	s_add_u32 s16, s42, 0x80
	s_addc_u32 s17, s43, 0
	s_cmp_eq_u32 s58, s44
	s_cselect_b32 s44, s0, s16
	s_cselect_b32 s45, s1, s17
	s_cselect_b32 s73, s41, s69
	s_cselect_b32 s72, s40, s68
	s_add_i32 m0, s50, 0xc000
	ds_read_b128 v[182:185], v149
	ds_read_b128 v[186:189], v149 offset:1024
	ds_read_b128 v[190:193], v149 offset:2048
	ds_read_b128 v[194:197], v149 offset:3072
	ds_read_b128 v[202:205], v149 offset:4096
	ds_read_b128 v[206:209], v149 offset:5120
	ds_read_b128 v[210:213], v149 offset:6144
	ds_read_b128 v[214:217], v149 offset:7168
	global_load_lds_dwordx4 v136, s[42:43]
	s_add_i32 m0, s50, 0xe000
	s_nop 0
	global_load_lds_dwordx4 v138, s[42:43]
	s_waitcnt vmcnt(8)
	s_waitcnt lgkmcnt(0)
	s_barrier
	s_setprio 1
	s_waitcnt lgkmcnt(0)
	v_mfma_f32_16x16x32_bf16 v[124:127], v[150:153], v[182:185], 0
	v_mfma_f32_16x16x32_bf16 v[116:119], v[158:161], v[182:185], 0
	v_mfma_f32_16x16x32_bf16 v[108:111], v[150:153], v[190:193], 0
	v_mfma_f32_16x16x32_bf16 v[100:103], v[158:161], v[190:193], 0
	v_mfma_f32_16x16x32_bf16 v[92:95], v[150:153], v[202:205], 0
	v_mfma_f32_16x16x32_bf16 v[84:87], v[158:161], v[202:205], 0
	v_mfma_f32_16x16x32_bf16 v[76:79], v[150:153], v[210:213], 0
	v_mfma_f32_16x16x32_bf16 v[68:71], v[158:161], v[210:213], 0
	v_mfma_f32_16x16x32_bf16 v[124:127], v[154:157], v[186:189], v[124:127]
	v_mfma_f32_16x16x32_bf16 v[116:119], v[162:165], v[186:189], v[116:119]
	v_mfma_f32_16x16x32_bf16 v[108:111], v[154:157], v[194:197], v[108:111]
	v_mfma_f32_16x16x32_bf16 v[100:103], v[162:165], v[194:197], v[100:103]
	v_mfma_f32_16x16x32_bf16 v[92:95], v[154:157], v[206:209], v[92:95]
	v_mfma_f32_16x16x32_bf16 v[84:87], v[162:165], v[206:209], v[84:87]
	v_mfma_f32_16x16x32_bf16 v[76:79], v[154:157], v[214:217], v[76:79]
	v_mfma_f32_16x16x32_bf16 v[68:71], v[162:165], v[214:217], v[68:71]
	s_setprio 0
	s_setprio 1
	v_mfma_f32_16x16x32_bf16 v[120:123], v[166:169], v[182:185], 0
	v_mfma_f32_16x16x32_bf16 v[112:115], v[174:177], v[182:185], 0
	v_mfma_f32_16x16x32_bf16 v[104:107], v[166:169], v[190:193], 0
	v_mfma_f32_16x16x32_bf16 v[96:99], v[174:177], v[190:193], 0
	v_mfma_f32_16x16x32_bf16 v[88:91], v[166:169], v[202:205], 0
	v_mfma_f32_16x16x32_bf16 v[80:83], v[174:177], v[202:205], 0
	v_mfma_f32_16x16x32_bf16 v[72:75], v[166:169], v[210:213], 0
	v_mfma_f32_16x16x32_bf16 v[64:67], v[174:177], v[210:213], 0
	v_mfma_f32_16x16x32_bf16 v[120:123], v[170:173], v[186:189], v[120:123]
	v_mfma_f32_16x16x32_bf16 v[112:115], v[178:181], v[186:189], v[112:115]
	v_mfma_f32_16x16x32_bf16 v[104:107], v[170:173], v[194:197], v[104:107]
	v_mfma_f32_16x16x32_bf16 v[96:99], v[178:181], v[194:197], v[96:99]
	v_mfma_f32_16x16x32_bf16 v[88:91], v[170:173], v[206:209], v[88:91]
	v_mfma_f32_16x16x32_bf16 v[80:83], v[178:181], v[206:209], v[80:83]
	v_mfma_f32_16x16x32_bf16 v[72:75], v[170:173], v[214:217], v[72:75]
	v_mfma_f32_16x16x32_bf16 v[64:67], v[178:181], v[214:217], v[64:67]
	s_setprio 0
	s_barrier
	s_add_i32 s16, s61, s47
	s_mov_b32 m0, s16
	ds_read_b128 v[182:185], v149 offset:16384
	ds_read_b128 v[186:189], v149 offset:17408
	ds_read_b128 v[190:193], v149 offset:18432
	ds_read_b128 v[194:197], v149 offset:19456
	ds_read_b128 v[202:205], v149 offset:20480
	ds_read_b128 v[206:209], v149 offset:21504
	ds_read_b128 v[210:213], v149 offset:22528
	ds_read_b128 v[214:217], v149 offset:23552
	global_load_lds_dwordx4 v132, s[72:73]
	s_add_i32 m0, s16, 0x2000
	s_add_i32 s16, s62, s47
	global_load_lds_dwordx4 v128, s[72:73]
	s_mov_b32 m0, s16
	s_nop 0
	global_load_lds_dwordx4 v198, s[72:73]
	s_add_i32 m0, s16, 0x2000
	s_nop 0
	global_load_lds_dwordx4 v199, s[72:73]
	s_mov_b32 m0, s50
	s_nop 0
	global_load_lds_dwordx4 v134, s[44:45]
	s_mov_b32 m0, s51
	s_nop 0
	global_load_lds_dwordx4 v130, s[44:45]
	s_waitcnt vmcnt(8)
	s_waitcnt lgkmcnt(0)
	s_barrier
; #define PG8_STAGE(bufoff, gbase, voff) do { _Pragma("unroll") for (int _i = 0; _i < 2; ++_i) \
;         __builtin_amdgcn_global_load_lds((const unsigned*)((const char*)(gbase) + (voff)[_i]), (PG8_LAS unsigned*)(lds + (bufoff) + ldsw + _i * 8192), 16, 0, 0); } while (0)
; #define PG8_LDA(dst, b, h) do { _Pragma("unroll") for (int m = 0; m < 4; ++m) _Pragma("unroll") for (int k = 0; k < 2; ++k) dst[m][k] = *(const PG8_LAS bf16x8*)(lds + PG8_SA(b, h) + aoff + m * 2048 + k * 1024); } while (0)
; #define PG8_LDB(dst, b, h) do { _Pragma("unroll") for (int n = 0; n < 2; ++n) _Pragma("unroll") for (int k = 0; k < 2; ++k) dst[n][k] = *(const PG8_LAS bf16x8*)(lds + PG8_SB(b, h) + boff + n * 2048 + k * 1024); } while (0)
; #define PG8_MMA(ai, bj, At, Bt) do { __builtin_amdgcn_s_setprio(1); _Pragma("unroll") for (int m = 0; m < 4; ++m) _Pragma("unroll") for (int n = 0; n < 2; ++n) _Pragma("unroll") for (int k = 0; k < 2; ++k) \
;         acc[ai][bj][m][n] = __builtin_amdgcn_mfma_f32_16x16x32_bf16(Bt[n][k], At[m][k], acc[ai][bj][m][n], 0, 0, 0); __builtin_amdgcn_s_setprio(0); } while (0)
; #define PG8_WAIT_V(n) asm volatile("s_waitcnt vmcnt(" #n ")" ::: "memory")
; #define PG8_WAIT_L(n) asm volatile("s_waitcnt lgkmcnt(" #n ")" ::: "memory")
; #define PG8_BAR __builtin_amdgcn_s_barrier()
; #define PG8_SCHED __builtin_amdgcn_sched_barrier(0)
; template <class Epi, class Sched, bool ALIGN_EPI = false, bool SP2 = false>
; __device__ __forceinline__ void gemm_phase(PG8_LAS unsigned char* lds, const Gemm g, const Sched& S, const Epi& E) {
;     ...
;             PG8_WAIT_V(8); PG8_WAIT_L(0); PG8_BAR; PG8_MMA(1, 0, At, B0); PG8_MMA(1, 1, At, B1); PG8_BAR; PG8_SCHED;
;             PG8_LDB(B0, 1, 0); PG8_LDB(B1, 1, 1); PG8_SCHED; PG8_LDA(At, 1, 0); PG8_STAGE(PG8_SA(0, 1), a2 + hstep, voffA);
;             PG8_WAIT_V(8); PG8_WAIT_L(0); PG8_BAR; PG8_MMA(0, 0, At, B0); PG8_MMA(0, 1, At, B1); PG8_BAR; PG8_SCHED;
	s_setprio 1
	s_waitcnt lgkmcnt(0)
	v_mfma_f32_16x16x32_bf16 v[60:63], v[150:153], v[182:185], 0
	v_mfma_f32_16x16x32_bf16 v[52:55], v[158:161], v[182:185], 0
	v_mfma_f32_16x16x32_bf16 v[44:47], v[150:153], v[190:193], 0
	v_mfma_f32_16x16x32_bf16 v[36:39], v[158:161], v[190:193], 0
	v_mfma_f32_16x16x32_bf16 v[28:31], v[150:153], v[202:205], 0
	v_mfma_f32_16x16x32_bf16 v[20:23], v[158:161], v[202:205], 0
	v_mfma_f32_16x16x32_bf16 v[12:15], v[150:153], v[210:213], 0
	v_mfma_f32_16x16x32_bf16 v[4:7], v[158:161], v[210:213], 0
	v_mfma_f32_16x16x32_bf16 v[60:63], v[154:157], v[186:189], v[60:63]
	v_mfma_f32_16x16x32_bf16 v[52:55], v[162:165], v[186:189], v[52:55]
	v_mfma_f32_16x16x32_bf16 v[44:47], v[154:157], v[194:197], v[44:47]
	v_mfma_f32_16x16x32_bf16 v[36:39], v[162:165], v[194:197], v[36:39]
	v_mfma_f32_16x16x32_bf16 v[28:31], v[154:157], v[206:209], v[28:31]
	v_mfma_f32_16x16x32_bf16 v[20:23], v[162:165], v[206:209], v[20:23]
	v_mfma_f32_16x16x32_bf16 v[12:15], v[154:157], v[214:217], v[12:15]
	v_mfma_f32_16x16x32_bf16 v[4:7], v[162:165], v[214:217], v[4:7]
	s_setprio 0
	s_setprio 1
	v_mfma_f32_16x16x32_bf16 v[56:59], v[166:169], v[182:185], 0
	v_mfma_f32_16x16x32_bf16 v[48:51], v[174:177], v[182:185], 0
	v_mfma_f32_16x16x32_bf16 v[40:43], v[166:169], v[190:193], 0
	v_mfma_f32_16x16x32_bf16 v[32:35], v[174:177], v[190:193], 0
	v_mfma_f32_16x16x32_bf16 v[24:27], v[166:169], v[202:205], 0
	v_mfma_f32_16x16x32_bf16 v[16:19], v[174:177], v[202:205], 0
	v_mfma_f32_16x16x32_bf16 v[8:11], v[166:169], v[210:213], 0
	v_mfma_f32_16x16x32_bf16 v[0:3], v[174:177], v[210:213], 0
	v_mfma_f32_16x16x32_bf16 v[56:59], v[170:173], v[186:189], v[56:59]
	v_mfma_f32_16x16x32_bf16 v[48:51], v[178:181], v[186:189], v[48:51]
	v_mfma_f32_16x16x32_bf16 v[40:43], v[170:173], v[194:197], v[40:43]
	v_mfma_f32_16x16x32_bf16 v[32:35], v[178:181], v[194:197], v[32:35]
	v_mfma_f32_16x16x32_bf16 v[24:27], v[170:173], v[206:209], v[24:27]
	v_mfma_f32_16x16x32_bf16 v[16:19], v[178:181], v[206:209], v[16:19]
	v_mfma_f32_16x16x32_bf16 v[8:11], v[170:173], v[214:217], v[8:11]
	v_mfma_f32_16x16x32_bf16 v[0:3], v[178:181], v[214:217], v[0:3]
	s_setprio 0
	s_barrier
	s_add_i32 s16, 0, 0x18000
	s_add_i32 s17, 0, 0x1c000
	v_add_u32_e32 v162, s16, v145
	v_add_u32_e32 v178, s17, v145
	ds_read_b128 v[150:153], v162
	ds_read_b128 v[154:157], v162 offset:1024
	ds_read_b128 v[158:161], v162 offset:2048
	ds_read_b128 v[162:165], v162 offset:3072
	ds_read_b128 v[166:169], v178
	ds_read_b128 v[170:173], v178 offset:1024
	ds_read_b128 v[174:177], v178 offset:2048
	ds_read_b128 v[178:181], v178 offset:3072
	s_mov_b32 m0, s52
	ds_read_b128 v[182:185], v149 offset:32768
	ds_read_b128 v[186:189], v149 offset:33792
	ds_read_b128 v[190:193], v149 offset:34816
	ds_read_b128 v[194:197], v149 offset:35840
	ds_read_b128 v[202:205], v149 offset:36864
	ds_read_b128 v[206:209], v149 offset:37888
	ds_read_b128 v[210:213], v149 offset:38912
	ds_read_b128 v[214:217], v149 offset:39936
	global_load_lds_dwordx4 v218, s[44:45]
	s_mov_b32 m0, s53
	s_nop 0
	global_load_lds_dwordx4 v219, s[44:45]
	s_waitcnt vmcnt(8)
	s_waitcnt lgkmcnt(0)
	s_barrier
	s_setprio 1
	s_waitcnt lgkmcnt(0)
	v_mfma_f32_16x16x32_bf16 v[124:127], v[150:153], v[182:185], v[124:127]
	v_mfma_f32_16x16x32_bf16 v[116:119], v[158:161], v[182:185], v[116:119]
	v_mfma_f32_16x16x32_bf16 v[108:111], v[150:153], v[190:193], v[108:111]
	v_mfma_f32_16x16x32_bf16 v[100:103], v[158:161], v[190:193], v[100:103]
	v_mfma_f32_16x16x32_bf16 v[92:95], v[150:153], v[202:205], v[92:95]
	v_mfma_f32_16x16x32_bf16 v[84:87], v[158:161], v[202:205], v[84:87]
	v_mfma_f32_16x16x32_bf16 v[76:79], v[150:153], v[210:213], v[76:79]
	v_mfma_f32_16x16x32_bf16 v[68:71], v[158:161], v[210:213], v[68:71]
	v_mfma_f32_16x16x32_bf16 v[124:127], v[154:157], v[186:189], v[124:127]
	v_mfma_f32_16x16x32_bf16 v[116:119], v[162:165], v[186:189], v[116:119]
	v_mfma_f32_16x16x32_bf16 v[108:111], v[154:157], v[194:197], v[108:111]
	v_mfma_f32_16x16x32_bf16 v[100:103], v[162:165], v[194:197], v[100:103]
	v_mfma_f32_16x16x32_bf16 v[92:95], v[154:157], v[206:209], v[92:95]
	v_mfma_f32_16x16x32_bf16 v[84:87], v[162:165], v[206:209], v[84:87]
	v_mfma_f32_16x16x32_bf16 v[76:79], v[154:157], v[214:217], v[76:79]
	v_mfma_f32_16x16x32_bf16 v[68:71], v[162:165], v[214:217], v[68:71]
	s_setprio 0
	s_setprio 1
	v_mfma_f32_16x16x32_bf16 v[120:123], v[166:169], v[182:185], v[120:123]
	v_mfma_f32_16x16x32_bf16 v[112:115], v[174:177], v[182:185], v[112:115]
	v_mfma_f32_16x16x32_bf16 v[104:107], v[166:169], v[190:193], v[104:107]
	v_mfma_f32_16x16x32_bf16 v[96:99], v[174:177], v[190:193], v[96:99]
	v_mfma_f32_16x16x32_bf16 v[88:91], v[166:169], v[202:205], v[88:91]
	v_mfma_f32_16x16x32_bf16 v[80:83], v[174:177], v[202:205], v[80:83]
	v_mfma_f32_16x16x32_bf16 v[72:75], v[166:169], v[210:213], v[72:75]
	v_mfma_f32_16x16x32_bf16 v[64:67], v[174:177], v[210:213], v[64:67]
	v_mfma_f32_16x16x32_bf16 v[120:123], v[170:173], v[186:189], v[120:123]
	v_mfma_f32_16x16x32_bf16 v[112:115], v[178:181], v[186:189], v[112:115]
	v_mfma_f32_16x16x32_bf16 v[104:107], v[170:173], v[194:197], v[104:107]
	v_mfma_f32_16x16x32_bf16 v[96:99], v[178:181], v[194:197], v[96:99]
	v_mfma_f32_16x16x32_bf16 v[88:91], v[170:173], v[206:209], v[88:91]
	v_mfma_f32_16x16x32_bf16 v[80:83], v[178:181], v[206:209], v[80:83]
	v_mfma_f32_16x16x32_bf16 v[72:75], v[170:173], v[214:217], v[72:75]
	v_mfma_f32_16x16x32_bf16 v[64:67], v[178:181], v[214:217], v[64:67]
	s_setprio 0
	s_barrier
; #define PG8_STAGE(bufoff, gbase, voff) do { _Pragma("unroll") for (int _i = 0; _i < 2; ++_i) \
;         __builtin_amdgcn_global_load_lds((const unsigned*)((const char*)(gbase) + (voff)[_i]), (PG8_LAS unsigned*)(lds + (bufoff) + ldsw + _i * 8192), 16, 0, 0); } while (0)
; #define PG8_LDA(dst, b, h) do { _Pragma("unroll") for (int m = 0; m < 4; ++m) _Pragma("unroll") for (int k = 0; k < 2; ++k) dst[m][k] = *(const PG8_LAS bf16x8*)(lds + PG8_SA(b, h) + aoff + m * 2048 + k * 1024); } while (0)
; #define PG8_MMA(ai, bj, At, Bt) do { __builtin_amdgcn_s_setprio(1); _Pragma("unroll") for (int m = 0; m < 4; ++m) _Pragma("unroll") for (int n = 0; n < 2; ++n) _Pragma("unroll") for (int k = 0; k < 2; ++k) \
;         acc[ai][bj][m][n] = __builtin_amdgcn_mfma_f32_16x16x32_bf16(Bt[n][k], At[m][k], acc[ai][bj][m][n], 0, 0, 0); __builtin_amdgcn_s_setprio(0); } while (0)
; #define PG8_WAIT_V(n) asm volatile("s_waitcnt vmcnt(" #n ")" ::: "memory")
; #define PG8_WAIT_L(n) asm volatile("s_waitcnt lgkmcnt(" #n ")" ::: "memory")
; #define PG8_BAR __builtin_amdgcn_s_barrier()
; #define PG8_SCHED __builtin_amdgcn_sched_barrier(0)
; template <class Epi, class Sched, bool ALIGN_EPI = false, bool SP2 = false>
; __device__ __forceinline__ void gemm_phase(PG8_LAS unsigned char* lds, const Gemm g, const Sched& S, const Epi& E) {
;     ...
;         for (int t = 0; t < nt; t += 2) {
;     ...
;             PG8_LDA(At, 1, 1); PG8_STAGE(PG8_SB(1, 0), b3, voffB); PG8_STAGE(PG8_SB(1, 1), b3 + hstep, voffB); PG8_STAGE(PG8_SA(1, 0), a3, voffA);
;             PG8_WAIT_V(8); PG8_WAIT_L(0); PG8_BAR; PG8_MMA(1, 0, At, B0); PG8_MMA(1, 1, At, B1); PG8_BAR; PG8_SCHED;
	s_add_i32 s16, s16, s47
	s_mov_b32 m0, s16
	ds_read_b128 v[182:185], v149 offset:49152
	ds_read_b128 v[186:189], v149 offset:50176
	ds_read_b128 v[190:193], v149 offset:51200
	ds_read_b128 v[194:197], v149 offset:52224
	ds_read_b128 v[202:205], v149 offset:53248
	ds_read_b128 v[206:209], v149 offset:54272
	ds_read_b128 v[210:213], v149 offset:55296
	ds_read_b128 v[214:217], v149 offset:56320
	global_load_lds_dwordx4 v220, s[72:73]
	s_add_i32 m0, s16, 0x2000
	s_add_i32 s16, s17, s47
	global_load_lds_dwordx4 v221, s[72:73]
	s_mov_b32 m0, s16
	s_nop 0
	global_load_lds_dwordx4 v222, s[72:73]
	s_add_i32 m0, s16, 0x2000
	s_nop 0
	global_load_lds_dwordx4 v223, s[72:73]
	s_mov_b32 m0, s55
	s_nop 0
	global_load_lds_dwordx4 v224, s[44:45]
	s_mov_b32 m0, s56
	s_nop 0
	global_load_lds_dwordx4 v225, s[44:45]
	s_waitcnt vmcnt(8)
	s_waitcnt lgkmcnt(0)
	s_barrier
	s_setprio 1
	s_waitcnt lgkmcnt(0)
	v_mfma_f32_16x16x32_bf16 v[60:63], v[150:153], v[182:185], v[60:63]
	v_mfma_f32_16x16x32_bf16 v[52:55], v[158:161], v[182:185], v[52:55]
	v_mfma_f32_16x16x32_bf16 v[44:47], v[150:153], v[190:193], v[44:47]
	v_mfma_f32_16x16x32_bf16 v[36:39], v[158:161], v[190:193], v[36:39]
	v_mfma_f32_16x16x32_bf16 v[28:31], v[150:153], v[202:205], v[28:31]
	v_mfma_f32_16x16x32_bf16 v[20:23], v[158:161], v[202:205], v[20:23]
	v_mfma_f32_16x16x32_bf16 v[12:15], v[150:153], v[210:213], v[12:15]
	v_mfma_f32_16x16x32_bf16 v[4:7], v[158:161], v[210:213], v[4:7]
	v_mfma_f32_16x16x32_bf16 v[60:63], v[154:157], v[186:189], v[60:63]
	v_mfma_f32_16x16x32_bf16 v[52:55], v[162:165], v[186:189], v[52:55]
	v_mfma_f32_16x16x32_bf16 v[44:47], v[154:157], v[194:197], v[44:47]
	v_mfma_f32_16x16x32_bf16 v[36:39], v[162:165], v[194:197], v[36:39]
	v_mfma_f32_16x16x32_bf16 v[28:31], v[154:157], v[206:209], v[28:31]
	v_mfma_f32_16x16x32_bf16 v[20:23], v[162:165], v[206:209], v[20:23]
	v_mfma_f32_16x16x32_bf16 v[12:15], v[154:157], v[214:217], v[12:15]
	v_mfma_f32_16x16x32_bf16 v[4:7], v[162:165], v[214:217], v[4:7]
	s_setprio 0
	s_setprio 1
	v_mfma_f32_16x16x32_bf16 v[56:59], v[166:169], v[182:185], v[56:59]
	v_mfma_f32_16x16x32_bf16 v[48:51], v[174:177], v[182:185], v[48:51]
	v_mfma_f32_16x16x32_bf16 v[40:43], v[166:169], v[190:193], v[40:43]
	v_mfma_f32_16x16x32_bf16 v[32:35], v[174:177], v[190:193], v[32:35]
	v_mfma_f32_16x16x32_bf16 v[24:27], v[166:169], v[202:205], v[24:27]
	v_mfma_f32_16x16x32_bf16 v[16:19], v[174:177], v[202:205], v[16:19]
	v_mfma_f32_16x16x32_bf16 v[8:11], v[166:169], v[210:213], v[8:11]
	v_mfma_f32_16x16x32_bf16 v[0:3], v[174:177], v[210:213], v[0:3]
	v_mfma_f32_16x16x32_bf16 v[56:59], v[170:173], v[186:189], v[56:59]
	v_mfma_f32_16x16x32_bf16 v[48:51], v[178:181], v[186:189], v[48:51]
	v_mfma_f32_16x16x32_bf16 v[40:43], v[170:173], v[194:197], v[40:43]
	v_mfma_f32_16x16x32_bf16 v[32:35], v[178:181], v[194:197], v[32:35]
	v_mfma_f32_16x16x32_bf16 v[24:27], v[170:173], v[206:209], v[24:27]
	v_mfma_f32_16x16x32_bf16 v[16:19], v[178:181], v[206:209], v[16:19]
	v_mfma_f32_16x16x32_bf16 v[8:11], v[170:173], v[214:217], v[8:11]
	v_mfma_f32_16x16x32_bf16 v[0:3], v[178:181], v[214:217], v[0:3]
	s_setprio 0
	s_barrier
	s_add_u32 s42, s42, 0x100
	s_addc_u32 s43, s43, 0
	s_add_u32 s68, s68, 0x100
	s_addc_u32 s69, s69, 0
	s_cmp_ge_i32 s70, s57
	s_mov_b32 s44, s70
	s_cbranch_scc1 .LBB0_1022

;     __device__ bool next(int i, Unit& u) const { if (!so.next(i >> 1, u)) return false; u.sel = i & 1; return true; }
; #define PG8_STAGE(bufoff, gbase, voff) do { _Pragma("unroll") for (int _i = 0; _i < 2; ++_i) \
;         __builtin_amdgcn_global_load_lds((const unsigned*)((const char*)(gbase) + (voff)[_i]), (PG8_LAS unsigned*)(lds + (bufoff) + ldsw + _i * 8192), 16, 0, 0); } while (0)
; #define PG8_LDA(dst, b, h) do { _Pragma("unroll") for (int m = 0; m < 4; ++m) _Pragma("unroll") for (int k = 0; k < 2; ++k) dst[m][k] = *(const PG8_LAS bf16x8*)(lds + PG8_SA(b, h) + aoff + m * 2048 + k * 1024); } while (0)
; #define PG8_LDB(dst, b, h) do { _Pragma("unroll") for (int n = 0; n < 2; ++n) _Pragma("unroll") for (int k = 0; k < 2; ++k) dst[n][k] = *(const PG8_LAS bf16x8*)(lds + PG8_SB(b, h) + boff + n * 2048 + k * 1024); } while (0)
; #define PG8_WAIT_V(n) asm volatile("s_waitcnt vmcnt(" #n ")" ::: "memory")
; #define PG8_BAR __builtin_amdgcn_s_barrier()
; template <class Epi, class Sched, bool ALIGN_EPI = false, bool SP2 = false>
; __device__ __forceinline__ void gemm_phase(PG8_LAS unsigned char* lds, const Gemm g, const Sched& S, const Epi& E) {
;     ...
;         const bool has_next = S.next(ui + 1, nxt);
;         const char* nA = has_next ? (const char*)(nxt.sel ? g.A2 : g.A) + (size_t)nxt.pm * tstep : cA; const char* nB = has_next ? (const char*)(nxt.sel ? g.Bt2 : g.Bt) + (size_t)nxt.pn * tstep : cB;
;         for (int t = 0; t < nt; t += 2) {
;             const bool last = (t == nt - 2);
;             const char* a1 = cA + (size_t)(t + 1) * kstep;
;             const char* a2 = last ? nA : cA + (size_t)(t + 2) * kstep; const char* b2 = last ? nB : cB + (size_t)(t + 2) * kstep;
;             const char* a3 = a2 + kstep; const char* b3 = b2 + kstep;
;             if (last && has_next) S.a_ready(nxt);
;             if constexpr (SP2) {
;             PG8_LDB(B0, 0, 0); PG8_LDB(B1, 0, 1); PG8_SCHED; PG8_LDA(At, 0, 0); PG8_STAGE(PG8_SA(1, 1), a1 + hstep, voffA);
;             PG8_WAIT_V(8); PG8_WAIT_L(0); PG8_BAR; PG8_MMA(0, 0, At, B0); PG8_MMA(0, 1, At, B1); PG8_BAR; PG8_SCHED;
;             PG8_LDA(At, 0, 1); PG8_STAGE(PG8_SB(0, 0), b2, voffB); PG8_STAGE(PG8_SB(0, 1), b2 + hstep, voffB); PG8_STAGE(PG8_SA(0, 0), a2, voffA);
;             PG8_WAIT_V(8); PG8_WAIT_L(0); PG8_BAR; PG8_MMA(1, 0, At, B0); PG8_MMA(1, 1, At, B1); PG8_BAR; PG8_SCHED;
.Lcz_go_1104:
	s_add_u32 s44, s44, 0x8000
	s_addc_u32 s45, s45, 0
	s_add_u32 s68, s46, 0x100
	s_addc_u32 s69, s47, 0
	s_mov_b32 s46, 0
	v_add_u32_e32 v218, s8, v130
	v_add_u32_e32 v219, s8, v134
	v_add_u32_e32 v220, 0x2000, v128
	v_add_u32_e32 v221, 0x2000, v132
	v_add_u32_e32 v222, 0x80, v130
	v_add_u32_e32 v223, 0x80, v134
	v_add_u32_e32 v224, 0x80, v218
	v_add_u32_e32 v225, 0x80, v219
	v_add_u32_e32 v226, 0x8000, v128
	v_add_u32_e32 v227, 0x8000, v132
	ds_read_b128 v[144:147], v151
	ds_read_b128 v[156:159], v151 offset:1024
	ds_read_b128 v[160:163], v151 offset:2048
	ds_read_b128 v[164:167], v151 offset:3072
	ds_read_b128 v[168:171], v152
	ds_read_b128 v[172:175], v152 offset:1024
	ds_read_b128 v[176:179], v152 offset:2048
	ds_read_b128 v[180:183], v152 offset:3072
	s_add_i32 s70, s46, 2
	s_add_u32 s16, s44, 0x8000
	s_addc_u32 s17, s45, 0
	s_cmp_eq_u32 s58, s46
	s_cselect_b32 s46, s0, s16
	s_cselect_b32 s47, s1, s17
	s_cselect_b32 s73, s43, s69
	s_cselect_b32 s72, s42, s68
	s_add_i32 m0, s50, 0xc000
	ds_read_b128 v[184:187], v153
	ds_read_b128 v[188:191], v153 offset:1024
	ds_read_b128 v[192:195], v153 offset:2048
	ds_read_b128 v[196:199], v153 offset:3072
	ds_read_b128 v[202:205], v153 offset:4096
	ds_read_b128 v[206:209], v153 offset:5120
	ds_read_b128 v[210:213], v153 offset:6144
	ds_read_b128 v[214:217], v153 offset:7168
	global_load_lds_dwordx4 v136, s[44:45]
	s_add_i32 m0, s50, 0xe000
	s_nop 0
	global_load_lds_dwordx4 v138, s[44:45]
	s_waitcnt vmcnt(8)
	s_waitcnt lgkmcnt(0)
	s_barrier
	s_setprio 1
	s_waitcnt lgkmcnt(0)
	v_mfma_f32_16x16x32_bf16 v[124:127], v[144:147], v[184:187], 0
	v_mfma_f32_16x16x32_bf16 v[120:123], v[160:163], v[184:187], 0
	v_mfma_f32_16x16x32_bf16 v[108:111], v[144:147], v[192:195], 0
	v_mfma_f32_16x16x32_bf16 v[104:107], v[160:163], v[192:195], 0
	v_mfma_f32_16x16x32_bf16 v[92:95], v[144:147], v[202:205], 0
	v_mfma_f32_16x16x32_bf16 v[88:91], v[160:163], v[202:205], 0
	v_mfma_f32_16x16x32_bf16 v[76:79], v[144:147], v[210:213], 0
	v_mfma_f32_16x16x32_bf16 v[72:75], v[160:163], v[210:213], 0
	v_mfma_f32_16x16x32_bf16 v[124:127], v[156:159], v[188:191], v[124:127]
	v_mfma_f32_16x16x32_bf16 v[120:123], v[164:167], v[188:191], v[120:123]
	v_mfma_f32_16x16x32_bf16 v[108:111], v[156:159], v[196:199], v[108:111]
	v_mfma_f32_16x16x32_bf16 v[104:107], v[164:167], v[196:199], v[104:107]
	v_mfma_f32_16x16x32_bf16 v[92:95], v[156:159], v[206:209], v[92:95]
	v_mfma_f32_16x16x32_bf16 v[88:91], v[164:167], v[206:209], v[88:91]
	v_mfma_f32_16x16x32_bf16 v[76:79], v[156:159], v[214:217], v[76:79]
	v_mfma_f32_16x16x32_bf16 v[72:75], v[164:167], v[214:217], v[72:75]
	s_setprio 0
	s_setprio 1
	v_mfma_f32_16x16x32_bf16 v[116:119], v[168:171], v[184:187], 0
	v_mfma_f32_16x16x32_bf16 v[112:115], v[176:179], v[184:187], 0
	v_mfma_f32_16x16x32_bf16 v[100:103], v[168:171], v[192:195], 0
	v_mfma_f32_16x16x32_bf16 v[96:99], v[176:179], v[192:195], 0
	v_mfma_f32_16x16x32_bf16 v[84:87], v[168:171], v[202:205], 0
	v_mfma_f32_16x16x32_bf16 v[80:83], v[176:179], v[202:205], 0
	v_mfma_f32_16x16x32_bf16 v[68:71], v[168:171], v[210:213], 0
	v_mfma_f32_16x16x32_bf16 v[64:67], v[176:179], v[210:213], 0
	v_mfma_f32_16x16x32_bf16 v[116:119], v[172:175], v[188:191], v[116:119]
	v_mfma_f32_16x16x32_bf16 v[112:115], v[180:183], v[188:191], v[112:115]
	v_mfma_f32_16x16x32_bf16 v[100:103], v[172:175], v[196:199], v[100:103]
	v_mfma_f32_16x16x32_bf16 v[96:99], v[180:183], v[196:199], v[96:99]
	v_mfma_f32_16x16x32_bf16 v[84:87], v[172:175], v[206:209], v[84:87]
	v_mfma_f32_16x16x32_bf16 v[80:83], v[180:183], v[206:209], v[80:83]
	v_mfma_f32_16x16x32_bf16 v[68:71], v[172:175], v[214:217], v[68:71]
	v_mfma_f32_16x16x32_bf16 v[64:67], v[180:183], v[214:217], v[64:67]
	s_setprio 0
	s_barrier
	s_add_i32 s16, s62, s49
	s_mov_b32 m0, s16
	ds_read_b128 v[184:187], v153 offset:16384
	ds_read_b128 v[188:191], v153 offset:17408
	ds_read_b128 v[192:195], v153 offset:18432
	ds_read_b128 v[196:199], v153 offset:19456
	ds_read_b128 v[202:205], v153 offset:20480
	ds_read_b128 v[206:209], v153 offset:21504
	ds_read_b128 v[210:213], v153 offset:22528
	ds_read_b128 v[214:217], v153 offset:23552
	global_load_lds_dwordx4 v130, s[72:73]
	s_add_i32 m0, s16, 0x2000
	s_add_i32 s16, s63, s49
	global_load_lds_dwordx4 v134, s[72:73]
	s_mov_b32 m0, s16
	s_nop 0
	global_load_lds_dwordx4 v218, s[72:73]
	s_add_i32 m0, s16, 0x2000
	s_nop 0
	global_load_lds_dwordx4 v219, s[72:73]
	s_mov_b32 m0, s50
	s_nop 0
	global_load_lds_dwordx4 v128, s[46:47]
	s_mov_b32 m0, s51
	s_nop 0
	global_load_lds_dwordx4 v132, s[46:47]
	s_waitcnt vmcnt(8)
	s_waitcnt lgkmcnt(0)
	s_barrier
; #define PG8_STAGE(bufoff, gbase, voff) do { _Pragma("unroll") for (int _i = 0; _i < 2; ++_i) \
;         __builtin_amdgcn_global_load_lds((const unsigned*)((const char*)(gbase) + (voff)[_i]), (PG8_LAS unsigned*)(lds + (bufoff) + ldsw + _i * 8192), 16, 0, 0); } while (0)
; #define PG8_LDA(dst, b, h) do { _Pragma("unroll") for (int m = 0; m < 4; ++m) _Pragma("unroll") for (int k = 0; k < 2; ++k) dst[m][k] = *(const PG8_LAS bf16x8*)(lds + PG8_SA(b, h) + aoff + m * 2048 + k * 1024); } while (0)
; #define PG8_LDB(dst, b, h) do { _Pragma("unroll") for (int n = 0; n < 2; ++n) _Pragma("unroll") for (int k = 0; k < 2; ++k) dst[n][k] = *(const PG8_LAS bf16x8*)(lds + PG8_SB(b, h) + boff + n * 2048 + k * 1024); } while (0)
; #define PG8_MMA(ai, bj, At, Bt) do { __builtin_amdgcn_s_setprio(1); _Pragma("unroll") for (int m = 0; m < 4; ++m) _Pragma("unroll") for (int n = 0; n < 2; ++n) _Pragma("unroll") for (int k = 0; k < 2; ++k) \
;         acc[ai][bj][m][n] = __builtin_amdgcn_mfma_f32_16x16x32_bf16(Bt[n][k], At[m][k], acc[ai][bj][m][n], 0, 0, 0); __builtin_amdgcn_s_setprio(0); } while (0)
; #define PG8_WAIT_V(n) asm volatile("s_waitcnt vmcnt(" #n ")" ::: "memory")
; #define PG8_WAIT_L(n) asm volatile("s_waitcnt lgkmcnt(" #n ")" ::: "memory")
; #define PG8_BAR __builtin_amdgcn_s_barrier()
; #define PG8_SCHED __builtin_amdgcn_sched_barrier(0)
; template <class Epi, class Sched, bool ALIGN_EPI = false, bool SP2 = false>
; __device__ __forceinline__ void gemm_phase(PG8_LAS unsigned char* lds, const Gemm g, const Sched& S, const Epi& E) {
;     ...
;             PG8_WAIT_V(8); PG8_WAIT_L(0); PG8_BAR; PG8_MMA(1, 0, At, B0); PG8_MMA(1, 1, At, B1); PG8_BAR; PG8_SCHED;
;             PG8_LDB(B0, 1, 0); PG8_LDB(B1, 1, 1); PG8_SCHED; PG8_LDA(At, 1, 0); PG8_STAGE(PG8_SA(0, 1), a2 + hstep, voffA);
;             PG8_WAIT_V(8); PG8_WAIT_L(0); PG8_BAR; PG8_MMA(0, 0, At, B0); PG8_MMA(0, 1, At, B1); PG8_BAR; PG8_SCHED;
	s_setprio 1
	s_waitcnt lgkmcnt(0)
	v_mfma_f32_16x16x32_bf16 v[60:63], v[144:147], v[184:187], 0
	v_mfma_f32_16x16x32_bf16 v[56:59], v[160:163], v[184:187], 0
	v_mfma_f32_16x16x32_bf16 v[44:47], v[144:147], v[192:195], 0
	v_mfma_f32_16x16x32_bf16 v[40:43], v[160:163], v[192:195], 0
	v_mfma_f32_16x16x32_bf16 v[28:31], v[144:147], v[202:205], 0
	v_mfma_f32_16x16x32_bf16 v[24:27], v[160:163], v[202:205], 0
	v_mfma_f32_16x16x32_bf16 v[12:15], v[144:147], v[210:213], 0
	v_mfma_f32_16x16x32_bf16 v[8:11], v[160:163], v[210:213], 0
	v_mfma_f32_16x16x32_bf16 v[60:63], v[156:159], v[188:191], v[60:63]
	v_mfma_f32_16x16x32_bf16 v[56:59], v[164:167], v[188:191], v[56:59]
	v_mfma_f32_16x16x32_bf16 v[44:47], v[156:159], v[196:199], v[44:47]
	v_mfma_f32_16x16x32_bf16 v[40:43], v[164:167], v[196:199], v[40:43]
	v_mfma_f32_16x16x32_bf16 v[28:31], v[156:159], v[206:209], v[28:31]
	v_mfma_f32_16x16x32_bf16 v[24:27], v[164:167], v[206:209], v[24:27]
	v_mfma_f32_16x16x32_bf16 v[12:15], v[156:159], v[214:217], v[12:15]
	v_mfma_f32_16x16x32_bf16 v[8:11], v[164:167], v[214:217], v[8:11]
	s_setprio 0
	s_setprio 1
	v_mfma_f32_16x16x32_bf16 v[52:55], v[168:171], v[184:187], 0
	v_mfma_f32_16x16x32_bf16 v[48:51], v[176:179], v[184:187], 0
	v_mfma_f32_16x16x32_bf16 v[36:39], v[168:171], v[192:195], 0
	v_mfma_f32_16x16x32_bf16 v[32:35], v[176:179], v[192:195], 0
	v_mfma_f32_16x16x32_bf16 v[20:23], v[168:171], v[202:205], 0
	v_mfma_f32_16x16x32_bf16 v[16:19], v[176:179], v[202:205], 0
	v_mfma_f32_16x16x32_bf16 v[4:7], v[168:171], v[210:213], 0
	v_mfma_f32_16x16x32_bf16 v[0:3], v[176:179], v[210:213], 0
	v_mfma_f32_16x16x32_bf16 v[52:55], v[172:175], v[188:191], v[52:55]
	v_mfma_f32_16x16x32_bf16 v[48:51], v[180:183], v[188:191], v[48:51]
	v_mfma_f32_16x16x32_bf16 v[36:39], v[172:175], v[196:199], v[36:39]
	v_mfma_f32_16x16x32_bf16 v[32:35], v[180:183], v[196:199], v[32:35]
	v_mfma_f32_16x16x32_bf16 v[20:23], v[172:175], v[206:209], v[20:23]
	v_mfma_f32_16x16x32_bf16 v[16:19], v[180:183], v[206:209], v[16:19]
	v_mfma_f32_16x16x32_bf16 v[4:7], v[172:175], v[214:217], v[4:7]
	v_mfma_f32_16x16x32_bf16 v[0:3], v[180:183], v[214:217], v[0:3]
	s_setprio 0
	s_barrier
	s_add_i32 s16, 0, 0x18000
	v_add_u32_e32 v155, s16, v149
	s_add_i32 s17, 0, 0x1c000
	ds_read_b128 v[144:147], v155
	ds_read_b128 v[156:159], v155 offset:1024
	ds_read_b128 v[160:163], v155 offset:2048
	ds_read_b128 v[164:167], v155 offset:3072
	v_add_u32_e32 v155, s17, v149
	ds_read_b128 v[168:171], v155
	ds_read_b128 v[172:175], v155 offset:1024
	ds_read_b128 v[176:179], v155 offset:2048
	ds_read_b128 v[180:183], v155 offset:3072
	s_mov_b32 m0, s52
	ds_read_b128 v[184:187], v153 offset:32768
	ds_read_b128 v[188:191], v153 offset:33792
	ds_read_b128 v[192:195], v153 offset:34816
	ds_read_b128 v[196:199], v153 offset:35840
	ds_read_b128 v[202:205], v153 offset:36864
	ds_read_b128 v[206:209], v153 offset:37888
	ds_read_b128 v[210:213], v153 offset:38912
	ds_read_b128 v[214:217], v153 offset:39936
	global_load_lds_dwordx4 v220, s[46:47]
	s_mov_b32 m0, s53
	s_nop 0
	global_load_lds_dwordx4 v221, s[46:47]
	s_waitcnt vmcnt(8)
	s_waitcnt lgkmcnt(0)
	s_barrier
	s_setprio 1
	s_waitcnt lgkmcnt(0)
	v_mfma_f32_16x16x32_bf16 v[124:127], v[144:147], v[184:187], v[124:127]
	v_mfma_f32_16x16x32_bf16 v[120:123], v[160:163], v[184:187], v[120:123]
	v_mfma_f32_16x16x32_bf16 v[108:111], v[144:147], v[192:195], v[108:111]
	v_mfma_f32_16x16x32_bf16 v[104:107], v[160:163], v[192:195], v[104:107]
	v_mfma_f32_16x16x32_bf16 v[92:95], v[144:147], v[202:205], v[92:95]
	v_mfma_f32_16x16x32_bf16 v[88:91], v[160:163], v[202:205], v[88:91]
	v_mfma_f32_16x16x32_bf16 v[76:79], v[144:147], v[210:213], v[76:79]
	v_mfma_f32_16x16x32_bf16 v[72:75], v[160:163], v[210:213], v[72:75]
	v_mfma_f32_16x16x32_bf16 v[124:127], v[156:159], v[188:191], v[124:127]
	v_mfma_f32_16x16x32_bf16 v[120:123], v[164:167], v[188:191], v[120:123]
	v_mfma_f32_16x16x32_bf16 v[108:111], v[156:159], v[196:199], v[108:111]
	v_mfma_f32_16x16x32_bf16 v[104:107], v[164:167], v[196:199], v[104:107]
	v_mfma_f32_16x16x32_bf16 v[92:95], v[156:159], v[206:209], v[92:95]
	v_mfma_f32_16x16x32_bf16 v[88:91], v[164:167], v[206:209], v[88:91]
	v_mfma_f32_16x16x32_bf16 v[76:79], v[156:159], v[214:217], v[76:79]
	v_mfma_f32_16x16x32_bf16 v[72:75], v[164:167], v[214:217], v[72:75]
	s_setprio 0
	s_setprio 1
	v_mfma_f32_16x16x32_bf16 v[116:119], v[168:171], v[184:187], v[116:119]
	v_mfma_f32_16x16x32_bf16 v[112:115], v[176:179], v[184:187], v[112:115]
	v_mfma_f32_16x16x32_bf16 v[100:103], v[168:171], v[192:195], v[100:103]
	v_mfma_f32_16x16x32_bf16 v[96:99], v[176:179], v[192:195], v[96:99]
	v_mfma_f32_16x16x32_bf16 v[84:87], v[168:171], v[202:205], v[84:87]
	v_mfma_f32_16x16x32_bf16 v[80:83], v[176:179], v[202:205], v[80:83]
	v_mfma_f32_16x16x32_bf16 v[68:71], v[168:171], v[210:213], v[68:71]
	v_mfma_f32_16x16x32_bf16 v[64:67], v[176:179], v[210:213], v[64:67]
	v_mfma_f32_16x16x32_bf16 v[116:119], v[172:175], v[188:191], v[116:119]
	v_mfma_f32_16x16x32_bf16 v[112:115], v[180:183], v[188:191], v[112:115]
	v_mfma_f32_16x16x32_bf16 v[100:103], v[172:175], v[196:199], v[100:103]
	v_mfma_f32_16x16x32_bf16 v[96:99], v[180:183], v[196:199], v[96:99]
	v_mfma_f32_16x16x32_bf16 v[84:87], v[172:175], v[206:209], v[84:87]
	v_mfma_f32_16x16x32_bf16 v[80:83], v[180:183], v[206:209], v[80:83]
	v_mfma_f32_16x16x32_bf16 v[68:71], v[172:175], v[214:217], v[68:71]
	v_mfma_f32_16x16x32_bf16 v[64:67], v[180:183], v[214:217], v[64:67]
	s_setprio 0
	s_barrier
; #define PG8_STAGE(bufoff, gbase, voff) do { _Pragma("unroll") for (int _i = 0; _i < 2; ++_i) \
;         __builtin_amdgcn_global_load_lds((const unsigned*)((const char*)(gbase) + (voff)[_i]), (PG8_LAS unsigned*)(lds + (bufoff) + ldsw + _i * 8192), 16, 0, 0); } while (0)
; #define PG8_LDA(dst, b, h) do { _Pragma("unroll") for (int m = 0; m < 4; ++m) _Pragma("unroll") for (int k = 0; k < 2; ++k) dst[m][k] = *(const PG8_LAS bf16x8*)(lds + PG8_SA(b, h) + aoff + m * 2048 + k * 1024); } while (0)
; #define PG8_MMA(ai, bj, At, Bt) do { __builtin_amdgcn_s_setprio(1); _Pragma("unroll") for (int m = 0; m < 4; ++m) _Pragma("unroll") for (int n = 0; n < 2; ++n) _Pragma("unroll") for (int k = 0; k < 2; ++k) \
;         acc[ai][bj][m][n] = __builtin_amdgcn_mfma_f32_16x16x32_bf16(Bt[n][k], At[m][k], acc[ai][bj][m][n], 0, 0, 0); __builtin_amdgcn_s_setprio(0); } while (0)
; #define PG8_WAIT_V(n) asm volatile("s_waitcnt vmcnt(" #n ")" ::: "memory")
; #define PG8_WAIT_L(n) asm volatile("s_waitcnt lgkmcnt(" #n ")" ::: "memory")
; #define PG8_BAR __builtin_amdgcn_s_barrier()
; #define PG8_SCHED __builtin_amdgcn_sched_barrier(0)
; template <class Epi, class Sched, bool ALIGN_EPI = false, bool SP2 = false>
; __device__ __forceinline__ void gemm_phase(PG8_LAS unsigned char* lds, const Gemm g, const Sched& S, const Epi& E) {
;     ...
;         for (int t = 0; t < nt; t += 2) {
;     ...
;             PG8_LDA(At, 1, 1); PG8_STAGE(PG8_SB(1, 0), b3, voffB); PG8_STAGE(PG8_SB(1, 1), b3 + hstep, voffB); PG8_STAGE(PG8_SA(1, 0), a3, voffA);
;             PG8_WAIT_V(8); PG8_WAIT_L(0); PG8_BAR; PG8_MMA(1, 0, At, B0); PG8_MMA(1, 1, At, B1); PG8_BAR; PG8_SCHED;
	s_add_i32 s16, s16, s49
	s_mov_b32 m0, s16
	ds_read_b128 v[184:187], v153 offset:49152
	ds_read_b128 v[188:191], v153 offset:50176
	ds_read_b128 v[192:195], v153 offset:51200
	ds_read_b128 v[196:199], v153 offset:52224
	ds_read_b128 v[202:205], v153 offset:53248
	ds_read_b128 v[206:209], v153 offset:54272
	ds_read_b128 v[210:213], v153 offset:55296
	ds_read_b128 v[214:217], v153 offset:56320
	global_load_lds_dwordx4 v222, s[72:73]
	s_add_i32 m0, s16, 0x2000
	s_add_i32 s16, s17, s49
	global_load_lds_dwordx4 v223, s[72:73]
	s_mov_b32 m0, s16
	s_nop 0
	global_load_lds_dwordx4 v224, s[72:73]
	s_add_i32 m0, s16, 0x2000
	s_nop 0
	global_load_lds_dwordx4 v225, s[72:73]
	s_mov_b32 m0, s54
	s_nop 0
	global_load_lds_dwordx4 v226, s[46:47]
	s_mov_b32 m0, s55
	s_nop 0
	global_load_lds_dwordx4 v227, s[46:47]
	s_waitcnt vmcnt(8)
	s_waitcnt lgkmcnt(0)
	s_barrier
	s_setprio 1
	s_waitcnt lgkmcnt(0)
	v_mfma_f32_16x16x32_bf16 v[60:63], v[144:147], v[184:187], v[60:63]
	v_mfma_f32_16x16x32_bf16 v[56:59], v[160:163], v[184:187], v[56:59]
	v_mfma_f32_16x16x32_bf16 v[44:47], v[144:147], v[192:195], v[44:47]
	v_mfma_f32_16x16x32_bf16 v[40:43], v[160:163], v[192:195], v[40:43]
	v_mfma_f32_16x16x32_bf16 v[28:31], v[144:147], v[202:205], v[28:31]
	v_mfma_f32_16x16x32_bf16 v[24:27], v[160:163], v[202:205], v[24:27]
	v_mfma_f32_16x16x32_bf16 v[12:15], v[144:147], v[210:213], v[12:15]
	v_mfma_f32_16x16x32_bf16 v[8:11], v[160:163], v[210:213], v[8:11]
	v_mfma_f32_16x16x32_bf16 v[60:63], v[156:159], v[188:191], v[60:63]
	v_mfma_f32_16x16x32_bf16 v[56:59], v[164:167], v[188:191], v[56:59]
	v_mfma_f32_16x16x32_bf16 v[44:47], v[156:159], v[196:199], v[44:47]
	v_mfma_f32_16x16x32_bf16 v[40:43], v[164:167], v[196:199], v[40:43]
	v_mfma_f32_16x16x32_bf16 v[28:31], v[156:159], v[206:209], v[28:31]
	v_mfma_f32_16x16x32_bf16 v[24:27], v[164:167], v[206:209], v[24:27]
	v_mfma_f32_16x16x32_bf16 v[12:15], v[156:159], v[214:217], v[12:15]
	v_mfma_f32_16x16x32_bf16 v[8:11], v[164:167], v[214:217], v[8:11]
	s_setprio 0
	s_setprio 1
	v_mfma_f32_16x16x32_bf16 v[52:55], v[168:171], v[184:187], v[52:55]
	v_mfma_f32_16x16x32_bf16 v[48:51], v[176:179], v[184:187], v[48:51]
	v_mfma_f32_16x16x32_bf16 v[36:39], v[168:171], v[192:195], v[36:39]
	v_mfma_f32_16x16x32_bf16 v[32:35], v[176:179], v[192:195], v[32:35]
	v_mfma_f32_16x16x32_bf16 v[20:23], v[168:171], v[202:205], v[20:23]
	v_mfma_f32_16x16x32_bf16 v[16:19], v[176:179], v[202:205], v[16:19]
	v_mfma_f32_16x16x32_bf16 v[4:7], v[168:171], v[210:213], v[4:7]
	v_mfma_f32_16x16x32_bf16 v[0:3], v[176:179], v[210:213], v[0:3]
	v_mfma_f32_16x16x32_bf16 v[52:55], v[172:175], v[188:191], v[52:55]
	v_mfma_f32_16x16x32_bf16 v[48:51], v[180:183], v[188:191], v[48:51]
	v_mfma_f32_16x16x32_bf16 v[36:39], v[172:175], v[196:199], v[36:39]
	v_mfma_f32_16x16x32_bf16 v[32:35], v[180:183], v[196:199], v[32:35]
	v_mfma_f32_16x16x32_bf16 v[20:23], v[172:175], v[206:209], v[20:23]
	v_mfma_f32_16x16x32_bf16 v[16:19], v[180:183], v[206:209], v[16:19]
	v_mfma_f32_16x16x32_bf16 v[4:7], v[172:175], v[214:217], v[4:7]
	v_mfma_f32_16x16x32_bf16 v[0:3], v[180:183], v[214:217], v[0:3]
	s_setprio 0
	s_barrier
	s_add_u32 s44, s44, 0x10000
	s_addc_u32 s45, s45, 0
	s_add_u32 s68, s68, 0x100
	s_addc_u32 s69, s69, 0
	s_cmp_ge_i32 s70, s57
	s_mov_b32 s46, s70
	s_cbranch_scc1 .LBB0_1105
